# GQA attention loop hand-written as a software pipeline (QK of tile t+1 under exp of tile t, PV of tile t under max/sum), 3 LDS buffers, unrolled x6
# speedup vs baseline: 1.0049x; 1.0049x over previous
; DI int TIDX() { int t = threadIdx.x; asm volatile("" : "+v"(t)); return t; }
; template <int DK, bool MLA>
; DI void attn_item(const h16* __restrict__ Q, const h16* __restrict__ Kp, const h16* __restrict__ Kr, const h16* __restrict__ Vt,
;                   int kbeg, int kend, h16* __restrict__ out, h16* sm) {
;     ...
;   const int tid = TIDX(), lane = tid & 63, w = tid >> 6, r = lane & 31, hh = lane >> 5;
;   h16x8 qf[DK / 16];
;   {
;     const h16* qr = Q + (size_t)(w * 32 + r) * DK + hh * 8;
; #pragma unroll
;     for (int ks = 0; ks < DK / 16; ++ks) qf[ks] = *(const h16x8*)(qr + ks * 16);
;   }
;   f32x16 ot[2];
; #pragma unroll
;   for (int i = 0; i < 16; ++i) { ot[0][i] = 0.f; ot[1][i] = 0.f; }
;   float m = -1000.f, lsum = 0.f;
;   u32x4 rkA[NCH], rvA[2], rkB[NCH], rvB[2];
;     ...
;   const int ntile = (kend - kbeg) >> 6;
;   ATT_GLOAD(rkA, rvA, kbeg)
;   ATT_GLOAD(rkB, rvB, kbeg + 64)
;   auto tile = [&](int it, u32x4 (&RK)[NCH], u32x4 (&RV)[2]) {
;     h16* ksm = sm + (it & 1) * BUF;
;     h16* vsm = ksm + 64 * KS;
; #pragma unroll
;     for (int i = 0; i < NCH; ++i) {
;       const int c = tid + 256 * i, key = c / NKC, part = c % NKC;
;       *(u32x4*)(ksm + key * KS + part * 8) = RK[i];
;     }
; #pragma unroll
;     for (int i = 0; i < 2; ++i) {
;       const int c = tid + 256 * i, dv = c >> 3, kc = c & 7;
;       *(u32x4*)(vsm + dv * 72 + kc * 8) = RV[i];
;     }
;     __syncthreads();
;     if (it + 2 < ntile) ATT_GLOAD(RK, RV, kbeg + (it + 2) * 64)
.LBB0_2732:
	s_and_b32 s53, s27, 7
	s_or_b32 s11, s53, s13
	s_mov_b64 s[8:9], -1
	s_andn2_b64 vcc, exec, s[6:7]
	s_mul_i32 s27, s11, 0x1100
	s_cbranch_vccz .LBB0_2744
	v_mov_b32_e32 v12, v203
	s_add_i32 s6, s27, s10
	s_mov_b32 s7, s37
	s_movk_i32 s2, 0xffe0
	v_ashrrev_i32_e32 v0, 1, v12
	s_lshl_b64 s[6:7], s[6:7], 7
	s_waitcnt vmcnt(4)
	v_bfi_b32 v144, s2, v0, v12
	s_add_u32 s8, s21, s6
	s_waitcnt vmcnt(2)
	v_ashrrev_i32_e32 v145, 31, v144
	s_addc_u32 s9, s22, s7
	v_bfe_u32 v13, v12, 5, 1
	v_lshlrev_b64 v[2:3], 7, v[144:145]
	v_lshl_add_u64 v[2:3], s[8:9], 0, v[2:3]
	v_lshlrev_b32_e32 v0, 4, v13
	s_lshr_b32 s6, s53, 2
	v_lshl_add_u64 v[2:3], v[2:3], 0, v[0:1]
	s_or_b32 s6, s6, s14
	global_load_dwordx4 v[80:83], v[2:3], off
	global_load_dwordx4 v[84:87], v[2:3], off offset:32
	global_load_dwordx4 v[88:91], v[2:3], off offset:64
	global_load_dwordx4 v[92:95], v[2:3], off offset:96
	v_ashrrev_i32_e32 v2, 31, v12
	s_mul_i32 s38, s6, 0x88000
	v_lshrrev_b32_e32 v2, 29, v2
	v_add_u32_e32 v10, 0x100, v12
	s_add_u32 s6, s23, s38
	v_add_u32_e32 v8, v12, v2
	v_ashrrev_i32_e32 v2, 31, v10
	s_addc_u32 s7, s24, 0
	v_lshrrev_b32_e32 v2, 29, v2
	s_add_u32 s38, s25, s38
	v_add_u32_e32 v4, v10, v2
	s_addc_u32 s39, s48, 0
	v_ashrrev_i32_e32 v15, 3, v4
	s_or_b32 s9, s26, 64
	v_and_b32_e32 v4, -8, v4
	v_ashrrev_i32_e32 v14, 3, v8
	v_add_u32_e32 v2, s9, v15
	v_sub_u32_e32 v16, v10, v4
	v_and_b32_e32 v8, -8, v8
	s_sub_i32 s8, 0x1100, s26
	v_ashrrev_i32_e32 v3, 31, v2
	v_lshlrev_b32_e32 v4, 3, v16
	v_add_u32_e32 v6, s9, v14
	v_sub_u32_e32 v17, v12, v8
	s_lshr_b32 s8, s8, 6
	v_lshlrev_b64 v[2:3], 7, v[2:3]
	v_ashrrev_i32_e32 v5, 31, v4
	v_ashrrev_i32_e32 v7, 31, v6
	v_lshlrev_b32_e32 v8, 3, v17
	s_lshl_b32 s9, s26, 1
	v_lshl_add_u64 v[2:3], s[6:7], 0, v[2:3]
	v_lshlrev_b64 v[4:5], 1, v[4:5]
	v_lshlrev_b64 v[6:7], 7, v[6:7]
	v_ashrrev_i32_e32 v9, 31, v8
	s_add_u32 s38, s38, s9
	v_lshl_add_u64 v[2:3], v[2:3], 0, v[4:5]
	v_lshl_add_u64 v[6:7], s[6:7], 0, v[6:7]
	v_lshlrev_b64 v[8:9], 1, v[8:9]
	s_addc_u32 s39, s39, 0
	v_lshl_add_u64 v[6:7], v[6:7], 0, v[8:9]
	global_load_dwordx4 v[96:99], v[2:3], off
	global_load_dwordx4 v[100:103], v[6:7], off
	v_ashrrev_i32_e32 v18, 3, v10
	v_mov_b64_e32 v[2:3], s[38:39]
	s_movk_i32 s2, 0x2200
	v_lshlrev_b32_e32 v10, 4, v12
	v_ashrrev_i32_e32 v19, 3, v12
	v_add_u32_e32 v130, s26, v15
	v_mad_i64_i32 v[6:7], s[40:41], v18, s2, v[2:3]
	v_and_b32_e32 v10, 0x70, v10
	v_mov_b32_e32 v11, v1
	v_mad_i64_i32 v[2:3], s[40:41], v19, s2, v[2:3]
	v_add_u32_e32 v128, s26, v14
	v_lshl_add_u64 v[134:135], v[2:3], 0, v[10:11]
	v_lshl_add_u64 v[2:3], s[38:39], 0, v[10:11]
	v_ashrrev_i32_e32 v131, 31, v130
	v_mad_i64_i32 v[136:137], s[38:39], v18, s2, v[2:3]
	v_mad_i64_i32 v[138:139], s[38:39], v19, s2, v[2:3]
	v_lshlrev_b64 v[2:3], 7, v[130:131]
	v_ashrrev_i32_e32 v129, 31, v128
	v_lshl_add_u64 v[132:133], v[6:7], 0, v[10:11]
	v_lshl_add_u64 v[2:3], s[6:7], 0, v[2:3]
	v_lshlrev_b64 v[6:7], 7, v[128:129]
	v_lshl_add_u64 v[2:3], v[2:3], 0, v[4:5]
	v_lshl_add_u64 v[6:7], s[6:7], 0, v[6:7]
	global_load_dwordx4 v[104:107], v[132:133], off offset:128
	global_load_dwordx4 v[108:111], v[134:135], off offset:128
	global_load_dwordx4 v[112:115], v[136:137], off
	global_load_dwordx4 v[116:119], v[138:139], off
	v_lshl_add_u64 v[6:7], v[6:7], 0, v[8:9]
	global_load_dwordx4 v[120:123], v[2:3], off
	global_load_dwordx4 v[124:127], v[6:7], off
	v_and_b32_e32 v2, 31, v12
	v_mul_lo_u32 v3, v14, s28
	v_mul_u32_u24_e32 v2, 0x48, v2
	v_lshl_add_u32 v129, v17, 4, v3
	v_mul_lo_u32 v3, v15, s28
	v_mad_u64_u32 v[140:141], s[38:39], v19, s28, v[10:11]
	v_mad_u64_u32 v[142:143], s[38:39], v18, s28, v[10:11]
	v_lshlrev_b32_e32 v2, 1, v2
	v_mov_b32_e32 v14, v1
	v_mov_b32_e32 v15, v1
	v_lshl_add_u32 v131, v16, 4, v3
	v_lshl_add_u64 v[148:149], s[6:7], 0, v[8:9]
	v_lshl_add_u64 v[150:151], s[6:7], 0, v[4:5]
	v_add_u32_e32 v141, v2, v0
	s_waitcnt vmcnt(13)
	v_lshlrev_b32_e32 v146, 2, v13
	v_lshl_add_u32 v143, v13, 4, v2
	v_mov_b32_e32 v0, v1
	v_mov_b32_e32 v2, v1
	v_mov_b32_e32 v3, v1
	v_mov_b32_e32 v4, v1
	v_mov_b32_e32 v5, v1
	v_mov_b32_e32 v6, v1
	v_mov_b32_e32 v7, v1
	v_mov_b32_e32 v8, v1
	v_mov_b32_e32 v9, v1
	v_mov_b32_e32 v10, v1
	v_mov_b32_e32 v12, v1
	v_mov_b32_e32 v13, v1
	v_mov_b64_e32 v[30:31], v[14:15]
	v_mov_b64_e32 v[46:47], v[14:15]
	s_mov_b32 s9, 3
	s_waitcnt vmcnt(12)
	v_mov_b32_e32 v147, 0xc47a0000
	v_mov_b32_e32 v153, 0
	s_movk_i32 s6, 0xc0
	v_mov_b64_e32 v[28:29], v[12:13]
	v_mov_b64_e32 v[26:27], v[10:11]
	v_mov_b64_e32 v[24:25], v[8:9]
	v_mov_b64_e32 v[22:23], v[6:7]
	v_mov_b64_e32 v[20:21], v[4:5]
	v_mov_b64_e32 v[18:19], v[2:3]
	v_mov_b64_e32 v[16:17], v[0:1]
	v_mov_b64_e32 v[44:45], v[12:13]
	v_mov_b64_e32 v[42:43], v[10:11]
	v_mov_b64_e32 v[40:41], v[8:9]
	v_mov_b64_e32 v[38:39], v[6:7]
	v_mov_b64_e32 v[36:37], v[4:5]
	v_mov_b64_e32 v[34:35], v[2:3]
	v_mov_b64_e32 v[32:33], v[0:1]
	v_mov_b32_e32 v204, 0x447a0000
	v_mov_b32_e32 v205, 0x447a0000
	v_mov_b32_e32 v206, 0x447a0000
	v_mov_b32_e32 v207, 0x447a0000
	v_mov_b32_e32 v208, 0x447a0000
	v_mov_b32_e32 v209, 0x447a0000
	v_mov_b32_e32 v210, 0x447a0000
	v_mov_b32_e32 v211, 0x447a0000
	v_mov_b32_e32 v212, 0x447a0000
	v_mov_b32_e32 v213, 0x447a0000
	v_mov_b32_e32 v214, 0x447a0000
	v_mov_b32_e32 v215, 0x447a0000
	v_mov_b32_e32 v216, 0x447a0000
	v_mov_b32_e32 v217, 0x447a0000
	v_mov_b32_e32 v218, 0x447a0000
	v_mov_b32_e32 v219, 0x447a0000
	s_movk_i32 s40, 0x80
	v_add_u32_e32 v2, s40, v128
	v_ashrrev_i32_e32 v3, 31, v2
	v_add_u32_e32 v4, s40, v130
	v_lshlrev_b64 v[2:3], 7, v[2:3]
	v_ashrrev_i32_e32 v5, 31, v4
	v_lshl_add_u64 v[220:221], v[148:149], 0, v[2:3]
	v_lshlrev_b64 v[4:5], 7, v[4:5]
	v_lshl_add_u64 v[222:223], v[150:151], 0, v[4:5]
	v_mov_b32_e32 v228, 0x2000
	v_mov_b32_e32 v229, 0
	s_mov_b32 s38, 0
	s_waitcnt vmcnt(0)
	ds_write_b128 v129, v[124:127] offset:0
	ds_write_b128 v131, v[120:123] offset:0
	ds_write_b128 v140, v[116:119] offset:9216
	ds_write_b128 v142, v[112:115] offset:9216
	s_waitcnt lgkmcnt(0)
	s_movk_i32 s40, 0x100
	s_mov_b32 s41, 0
	global_load_dwordx4 v[124:127], v[220:221], off
	global_load_dwordx4 v[120:123], v[222:223], off
	v_lshl_add_u64 v[14:15], v[138:139], 0, s[40:41]
	v_lshl_add_u64 v[250:251], v[136:137], 0, s[40:41]
	global_load_dwordx4 v[116:119], v[14:15], off
	global_load_dwordx4 v[112:115], v[250:251], off
	v_lshl_add_u64 v[220:221], v[220:221], 0, v[228:229]
	v_lshl_add_u64 v[222:223], v[222:223], 0, v[228:229]
	s_barrier
; #define MFMA(a, b, c) __builtin_amdgcn_mfma_f32_32x32x16_f16((a), (b), (c), 0, 0, 0)
; template <int DK, bool MLA>
; DI void attn_item(const h16* __restrict__ Q, const h16* __restrict__ Kp, const h16* __restrict__ Kr, const h16* __restrict__ Vt,
;                   int kbeg, int kend, h16* __restrict__ out, h16* sm) {
;     ...
;     __syncthreads();
;     if (it + 2 < ntile) ATT_GLOAD(RK, RV, kbeg + (it + 2) * 64)
;     f32x16 st[2];
;     const float negm = -m;
; #pragma unroll
;     for (int i = 0; i < 16; ++i) { st[0][i] = negm; st[1][i] = negm; }
; #pragma unroll
;     for (int ks = 0; ks < DK / 16; ++ks) {
;       h16x8 k0 = *(const h16x8*)(ksm + r * KS + ks * 16 + hh * 8);
;       h16x8 k1 = *(const h16x8*)(ksm + (32 + r) * KS + ks * 16 + hh * 8);
;       st[0] = MFMA(k0, qf[ks], st[0]);
;       st[1] = MFMA(k1, qf[ks], st[1]);
;     }
;     float mx = fmaxf(st[0][0], st[1][0]);
; #pragma unroll
;     for (int i = 1; i < 16; ++i) mx = fmaxf(mx, fmaxf(st[0][i], st[1][i]));
;     mx = x32_max(mx);
;     if (__builtin_amdgcn_ballot_w64(mx > 8.f) != 0) {
;       const float dlt = fmaxf(mx, 0.f);
;       const float alpha = __builtin_amdgcn_exp2f(-dlt);
;       m += dlt;
;       lsum *= alpha;
; #pragma unroll
;       for (int i = 0; i < 16; ++i) { ot[0][i] *= alpha; ot[1][i] *= alpha; st[0][i] -= dlt; st[1][i] -= dlt; }
;     }
	ds_read_b128 v[194:197], v141 offset:0
	ds_read_b128 v[198:201], v141 offset:4608
	ds_read_b128 v[230:233], v141 offset:32
	ds_read_b128 v[234:237], v141 offset:4640
	s_waitcnt lgkmcnt(3)
	v_mfma_f32_32x32x16_f16 v[48:63], v[194:197], v[80:83], v[204:219]
	ds_read_b128 v[194:197], v141 offset:64
	s_waitcnt lgkmcnt(3)
	v_mfma_f32_32x32x16_f16 v[64:79], v[198:201], v[80:83], v[204:219]
	ds_read_b128 v[198:201], v141 offset:4672
	s_waitcnt lgkmcnt(3)
	v_mfma_f32_32x32x16_f16 v[48:63], v[230:233], v[84:87], v[48:63]
	ds_read_b128 v[230:233], v141 offset:96
	s_waitcnt lgkmcnt(3)
	v_mfma_f32_32x32x16_f16 v[64:79], v[234:237], v[84:87], v[64:79]
	ds_read_b128 v[234:237], v141 offset:4704
	s_waitcnt lgkmcnt(3)
	v_mfma_f32_32x32x16_f16 v[48:63], v[194:197], v[88:91], v[48:63]
	s_waitcnt lgkmcnt(2)
	v_mfma_f32_32x32x16_f16 v[64:79], v[198:201], v[88:91], v[64:79]
	s_waitcnt lgkmcnt(1)
	v_mfma_f32_32x32x16_f16 v[48:63], v[230:233], v[92:95], v[48:63]
	s_waitcnt lgkmcnt(0)
	v_mfma_f32_32x32x16_f16 v[64:79], v[234:237], v[92:95], v[64:79]
	ds_write_b128 v129, v[100:103] offset:18432
	ds_write_b128 v131, v[96:99] offset:18432
	ds_write_b128 v140, v[108:111] offset:27648
	ds_write_b128 v142, v[104:107] offset:27648
	s_waitcnt lgkmcnt(0)
	s_movk_i32 s40, 0x180
	s_mov_b32 s41, 0
	global_load_dwordx4 v[100:103], v[220:221], off
	global_load_dwordx4 v[96:99], v[222:223], off
	v_lshl_add_u64 v[14:15], v[134:135], 0, s[40:41]
	v_lshl_add_u64 v[250:251], v[132:133], 0, s[40:41]
	global_load_dwordx4 v[108:111], v[14:15], off
	global_load_dwordx4 v[104:107], v[250:251], off
	v_lshl_add_u64 v[220:221], v[220:221], 0, v[228:229]
	v_lshl_add_u64 v[222:223], v[222:223], 0, v[228:229]
	s_nop 7
	s_nop 7
	v_max3_f32 v0, v48, v49, v50
	v_max3_f32 v14, v51, v52, v53
	v_max3_f32 v15, v54, v55, v56
	v_max3_f32 v202, v57, v58, v59
	v_max3_f32 v0, v0, v60, v61
	v_max3_f32 v14, v14, v62, v63
	v_max3_f32 v15, v15, v64, v65
	v_max3_f32 v202, v202, v66, v67
	v_max3_f32 v0, v0, v68, v69
	v_max3_f32 v14, v14, v70, v71
	v_max3_f32 v15, v15, v72, v73
	v_max3_f32 v202, v202, v74, v75
	v_max3_f32 v0, v0, v76, v77
	v_max3_f32 v14, v14, v78, v79
	v_max3_f32 v0, v0, v14, v15
	v_max_f32_e32 v0, v0, v202
	v_mov_b32_e32 v14, v0
	s_nop 1
	v_permlane32_swap_b32_e32 v0, v14
	v_max_f32_e32 v0, v0, v14
	v_cmp_lt_f32_e32 vcc, s79, v0
	s_cbranch_vccnz .Lgq_rarepre
	s_branch .Lgq_step0
.Lgq_rarepre:
	s_nop 7
	s_nop 7
	s_nop 7
	v_max_f32_e32 v0, 0, v0
	v_exp_f32_e64 v14, -v0
	v_add_f32_e32 v147, v147, v0
	v_xor_b32_e32 v204, 0x80000000, v147
	v_mov_b32_e32 v205, v204
	v_mov_b32_e32 v206, v204
	v_mov_b32_e32 v207, v204
	v_mov_b32_e32 v208, v204
	v_mov_b32_e32 v209, v204
	v_mov_b32_e32 v210, v204
	v_mov_b32_e32 v211, v204
	v_mov_b32_e32 v212, v204
	v_mov_b32_e32 v213, v204
	v_mov_b32_e32 v214, v204
	v_mov_b32_e32 v215, v204
	v_mov_b32_e32 v216, v204
	v_mov_b32_e32 v217, v204
	v_mov_b32_e32 v218, v204
	v_mov_b32_e32 v219, v204
	v_mul_f32_e32 v153, v153, v14
	v_sub_f32_e32 v48, v48, v0
	v_sub_f32_e32 v49, v49, v0
	v_sub_f32_e32 v50, v50, v0
	v_sub_f32_e32 v51, v51, v0
	v_sub_f32_e32 v52, v52, v0
	v_sub_f32_e32 v53, v53, v0
	v_sub_f32_e32 v54, v54, v0
	v_sub_f32_e32 v55, v55, v0
	v_sub_f32_e32 v56, v56, v0
	v_sub_f32_e32 v57, v57, v0
	v_sub_f32_e32 v58, v58, v0
	v_sub_f32_e32 v59, v59, v0
	v_sub_f32_e32 v60, v60, v0
	v_sub_f32_e32 v61, v61, v0
	v_sub_f32_e32 v62, v62, v0
	v_sub_f32_e32 v63, v63, v0
	v_sub_f32_e32 v64, v64, v0
	v_sub_f32_e32 v65, v65, v0
	v_sub_f32_e32 v66, v66, v0
	v_sub_f32_e32 v67, v67, v0
	v_sub_f32_e32 v68, v68, v0
	v_sub_f32_e32 v69, v69, v0
	v_sub_f32_e32 v70, v70, v0
	v_sub_f32_e32 v71, v71, v0
	v_sub_f32_e32 v72, v72, v0
	v_sub_f32_e32 v73, v73, v0
	v_sub_f32_e32 v74, v74, v0
	v_sub_f32_e32 v75, v75, v0
	v_sub_f32_e32 v76, v76, v0
	v_sub_f32_e32 v77, v77, v0
	v_sub_f32_e32 v78, v78, v0
	v_sub_f32_e32 v79, v79, v0
	v_mul_f32_e32 v32, v32, v14
	v_mul_f32_e32 v33, v33, v14
	v_mul_f32_e32 v34, v34, v14
	v_mul_f32_e32 v35, v35, v14
	v_mul_f32_e32 v36, v36, v14
	v_mul_f32_e32 v37, v37, v14
	v_mul_f32_e32 v38, v38, v14
	v_mul_f32_e32 v39, v39, v14
	v_mul_f32_e32 v40, v40, v14
	v_mul_f32_e32 v41, v41, v14
	v_mul_f32_e32 v42, v42, v14
	v_mul_f32_e32 v43, v43, v14
	v_mul_f32_e32 v44, v44, v14
	v_mul_f32_e32 v45, v45, v14
	v_mul_f32_e32 v46, v46, v14
	v_mul_f32_e32 v47, v47, v14
	v_mul_f32_e32 v16, v16, v14
	v_mul_f32_e32 v17, v17, v14
	v_mul_f32_e32 v18, v18, v14
	v_mul_f32_e32 v19, v19, v14
	v_mul_f32_e32 v20, v20, v14
	v_mul_f32_e32 v21, v21, v14
	v_mul_f32_e32 v22, v22, v14
	v_mul_f32_e32 v23, v23, v14
	v_mul_f32_e32 v24, v24, v14
	v_mul_f32_e32 v25, v25, v14
	v_mul_f32_e32 v26, v26, v14
	v_mul_f32_e32 v27, v27, v14
	v_mul_f32_e32 v28, v28, v14
	v_mul_f32_e32 v29, v29, v14
	v_mul_f32_e32 v30, v30, v14
	v_mul_f32_e32 v31, v31, v14
	s_branch .Lgq_step0
; #define MFMA(a, b, c) __builtin_amdgcn_mfma_f32_32x32x16_f16((a), (b), (c), 0, 0, 0)
; template <int DK, bool MLA>
; DI void attn_item(const h16* __restrict__ Q, const h16* __restrict__ Kp, const h16* __restrict__ Kr, const h16* __restrict__ Vt,
;                   int kbeg, int kend, h16* __restrict__ out, h16* sm) {
;     ...
;     f32x16 st[2];
;     const float negm = -m;
; #pragma unroll
;     for (int i = 0; i < 16; ++i) { st[0][i] = negm; st[1][i] = negm; }
; #pragma unroll
;     for (int ks = 0; ks < DK / 16; ++ks) {
;       h16x8 k0 = *(const h16x8*)(ksm + r * KS + ks * 16 + hh * 8);
;       h16x8 k1 = *(const h16x8*)(ksm + (32 + r) * KS + ks * 16 + hh * 8);
;       st[0] = MFMA(k0, qf[ks], st[0]);
;       st[1] = MFMA(k1, qf[ks], st[1]);
;     }
;     float mx = fmaxf(st[0][0], st[1][0]);
; #pragma unroll
;     for (int i = 1; i < 16; ++i) mx = fmaxf(mx, fmaxf(st[0][i], st[1][i]));
;     mx = x32_max(mx);
;     if (__builtin_amdgcn_ballot_w64(mx > 8.f) != 0) {
;       const float dlt = fmaxf(mx, 0.f);
;       const float alpha = __builtin_amdgcn_exp2f(-dlt);
;       m += dlt;
;       lsum *= alpha;
; #pragma unroll
;       for (int i = 0; i < 16; ++i) { ot[0][i] *= alpha; ot[1][i] *= alpha; st[0][i] -= dlt; st[1][i] -= dlt; }
;     }
;     float ps = 0.f;
; #pragma unroll
;     for (int i = 0; i < 16; ++i) {
;       st[0][i] = __builtin_amdgcn_exp2f(st[0][i]);
;       st[1][i] = __builtin_amdgcn_exp2f(st[1][i]);
;       ps += st[0][i] + st[1][i];
;     }
;     lsum += ps;
; #pragma unroll
;     for (int s4 = 0; s4 < 4; ++s4) {
;       const int kt2 = s4 >> 1, hf = s4 & 1;
;       h16x8 pb;
; #pragma unroll
;       for (int j = 0; j < 8; ++j) pb[j] = (h16)st[kt2][8 * hf + j];
.Lgq_step0:
	s_waitcnt lgkmcnt(0)
	s_barrier
	ds_read_b128 v[194:197], v141 offset:18432
	ds_read_b128 v[198:201], v141 offset:23040
	ds_read_b128 v[230:233], v141 offset:18464
	ds_read_b128 v[234:237], v141 offset:23072
	v_exp_f32_e32 v48, v48
	v_exp_f32_e32 v49, v49
	v_exp_f32_e32 v50, v50
	v_exp_f32_e32 v51, v51
	s_waitcnt lgkmcnt(3)
	v_mfma_f32_32x32x16_f16 v[162:177], v[194:197], v[80:83], v[204:219]
	ds_read_b128 v[194:197], v141 offset:18496
	v_exp_f32_e32 v52, v52
	v_exp_f32_e32 v53, v53
	v_cvt_pk_f16_f32 v2, v48, v49
	v_exp_f32_e32 v54, v54
	v_exp_f32_e32 v55, v55
	v_cvt_pk_f16_f32 v3, v50, v51
	s_waitcnt lgkmcnt(3)
	v_mfma_f32_32x32x16_f16 v[178:193], v[198:201], v[80:83], v[204:219]
	ds_read_b128 v[198:201], v141 offset:23104
	v_exp_f32_e32 v56, v56
	v_exp_f32_e32 v57, v57
	v_cvt_pk_f16_f32 v4, v52, v53
	v_exp_f32_e32 v58, v58
	v_exp_f32_e32 v59, v59
	v_cvt_pk_f16_f32 v5, v54, v55
	s_waitcnt lgkmcnt(3)
	v_mfma_f32_32x32x16_f16 v[162:177], v[230:233], v[84:87], v[162:177]
	ds_read_b128 v[230:233], v141 offset:18528
	v_exp_f32_e32 v60, v60
	v_exp_f32_e32 v61, v61
	v_cvt_pk_f16_f32 v6, v56, v57
	v_exp_f32_e32 v62, v62
	v_exp_f32_e32 v63, v63
	v_cvt_pk_f16_f32 v7, v58, v59
	s_waitcnt lgkmcnt(3)
	v_mfma_f32_32x32x16_f16 v[178:193], v[234:237], v[84:87], v[178:193]
	ds_read_b128 v[234:237], v141 offset:23136
	v_exp_f32_e32 v64, v64
	v_exp_f32_e32 v65, v65
	v_cvt_pk_f16_f32 v8, v60, v61
	v_exp_f32_e32 v66, v66
	v_exp_f32_e32 v67, v67
	v_cvt_pk_f16_f32 v9, v62, v63
	s_waitcnt lgkmcnt(3)
	v_mfma_f32_32x32x16_f16 v[162:177], v[194:197], v[88:91], v[162:177]
	v_exp_f32_e32 v68, v68
	v_exp_f32_e32 v69, v69
	v_cvt_pk_f16_f32 v10, v64, v65
	v_exp_f32_e32 v70, v70
	v_exp_f32_e32 v71, v71
	v_cvt_pk_f16_f32 v11, v66, v67
	s_waitcnt lgkmcnt(2)
	v_mfma_f32_32x32x16_f16 v[178:193], v[198:201], v[88:91], v[178:193]
	v_exp_f32_e32 v72, v72
	v_exp_f32_e32 v73, v73
	v_cvt_pk_f16_f32 v12, v68, v69
	v_exp_f32_e32 v74, v74
	v_exp_f32_e32 v75, v75
	v_cvt_pk_f16_f32 v13, v70, v71
	s_waitcnt lgkmcnt(1)
	v_mfma_f32_32x32x16_f16 v[162:177], v[230:233], v[92:95], v[162:177]
	v_exp_f32_e32 v76, v76
	v_exp_f32_e32 v77, v77
	v_cvt_pk_f16_f32 v246, v72, v73
	v_exp_f32_e32 v78, v78
	v_exp_f32_e32 v79, v79
	v_cvt_pk_f16_f32 v247, v74, v75
	s_waitcnt lgkmcnt(0)
	v_mfma_f32_32x32x16_f16 v[178:193], v[234:237], v[92:95], v[178:193]
	v_cvt_pk_f16_f32 v248, v76, v77
	v_cvt_pk_f16_f32 v249, v78, v79
	s_add_i32 s40, s38, 2
	s_cmp_ge_u32 s40, s8
	s_cbranch_scc1 .Lgq_nw0
	s_add_i32 s40, s38, 3
	s_cmp_ge_u32 s40, s8
	s_cbranch_scc1 .Lgq_wz0
	s_waitcnt vmcnt(4)
	s_branch .Lgq_ww0

; #define MFMA(a, b, c) __builtin_amdgcn_mfma_f32_32x32x16_f16((a), (b), (c), 0, 0, 0)
; template <int DK, bool MLA>
; DI void attn_item(const h16* __restrict__ Q, const h16* __restrict__ Kp, const h16* __restrict__ Kr, const h16* __restrict__ Vt,
;                   int kbeg, int kend, h16* __restrict__ out, h16* sm) {
;     ...
;       *(u32x4*)(ksm + key * KS + part * 8) = RK[i];
;     }
; #pragma unroll
;     for (int i = 0; i < 2; ++i) {
;       const int c = tid + 256 * i, dv = c >> 3, kc = c & 7;
;       *(u32x4*)(vsm + dv * 72 + kc * 8) = RV[i];
;     }
;     __syncthreads();
;     if (it + 2 < ntile) ATT_GLOAD(RK, RV, kbeg + (it + 2) * 64)
;     f32x16 st[2];
;     const float negm = -m;
; #pragma unroll
;     for (int i = 0; i < 16; ++i) { st[0][i] = negm; st[1][i] = negm; }
; #pragma unroll
;     for (int ks = 0; ks < DK / 16; ++ks) {
;       h16x8 k0 = *(const h16x8*)(ksm + r * KS + ks * 16 + hh * 8);
;       h16x8 k1 = *(const h16x8*)(ksm + (32 + r) * KS + ks * 16 + hh * 8);
;       st[0] = MFMA(k0, qf[ks], st[0]);
;       st[1] = MFMA(k1, qf[ks], st[1]);
;     }
;     float mx = fmaxf(st[0][0], st[1][0]);
; #pragma unroll
;     for (int i = 1; i < 16; ++i) mx = fmaxf(mx, fmaxf(st[0][i], st[1][i]));
;     mx = x32_max(mx);
;     if (__builtin_amdgcn_ballot_w64(mx > 8.f) != 0) {
;       const float dlt = fmaxf(mx, 0.f);
;       const float alpha = __builtin_amdgcn_exp2f(-dlt);
;       m += dlt;
;       lsum *= alpha;
; #pragma unroll
;       for (int i = 0; i < 16; ++i) { ot[0][i] *= alpha; ot[1][i] *= alpha; st[0][i] -= dlt; st[1][i] -= dlt; }
;     }
;     float ps = 0.f;
; #pragma unroll
;     for (int i = 0; i < 16; ++i) {
;       st[0][i] = __builtin_amdgcn_exp2f(st[0][i]);
;       st[1][i] = __builtin_amdgcn_exp2f(st[1][i]);
;       ps += st[0][i] + st[1][i];
;     }
;     lsum += ps;
; #pragma unroll
;     for (int s4 = 0; s4 < 4; ++s4) {
;       const int kt2 = s4 >> 1, hf = s4 & 1;
;       h16x8 pb;
; #pragma unroll
;       for (int j = 0; j < 8; ++j) pb[j] = (h16)st[kt2][8 * hf + j];
;       const int kb = kt2 * 32 + 16 * hf;
; #pragma unroll
;       for (int dt = 0; dt < 2; ++dt) {
;         const h16* vp = vsm + (dt * 32 + r) * 72 + kb + 4 * hh;
;         h16x4 lo = *(const h16x4*)vp, hi = *(const h16x4*)(vp + 8);
;         h16x8 va = __builtin_shufflevector(lo, hi, 0, 1, 2, 3, 4, 5, 6, 7);
;         ot[dt] = MFMA(va, pb, ot[dt]);
;       }
.Lgq_ww0:
	ds_write_b128 v129, v[124:127] offset:36864
	ds_write_b128 v131, v[120:123] offset:36864
	ds_write_b128 v140, v[116:119] offset:46080
	ds_write_b128 v142, v[112:115] offset:46080
.Lgq_nw0:
	ds_read_b128 v[238:241], v143 offset:9216
	ds_read_b128 v[242:245], v143 offset:13824
	ds_read_b128 v[194:197], v143 offset:9248
	ds_read_b128 v[198:201], v143 offset:13856
	s_waitcnt lgkmcnt(3)
	v_mfma_f32_32x32x16_f16 v[32:47], v[238:241], v[2:5], v[32:47]
	ds_read_b128 v[238:241], v143 offset:9280
	s_add_i32 s40, s38, 4
	s_cmp_ge_u32 s40, s8
	s_cbranch_scc1 .Lgq_nl0
	s_lshl_b32 s40, s40, 7
	s_mov_b32 s41, 0
	global_load_dwordx4 v[124:127], v[220:221], off
	global_load_dwordx4 v[120:123], v[222:223], off
	v_lshl_add_u64 v[14:15], v[138:139], 0, s[40:41]
	v_lshl_add_u64 v[250:251], v[136:137], 0, s[40:41]
	global_load_dwordx4 v[116:119], v[14:15], off
	global_load_dwordx4 v[112:115], v[250:251], off
	v_lshl_add_u64 v[220:221], v[220:221], 0, v[228:229]
	v_lshl_add_u64 v[222:223], v[222:223], 0, v[228:229]
.Lgq_nl0:
	v_add_f32_e32 v226, v48, v49
	v_add_f32_e32 v226, v226, v50
	v_add_f32_e32 v226, v226, v51
	v_add_f32_e32 v226, v226, v52
	s_waitcnt lgkmcnt(3)
	v_mfma_f32_32x32x16_f16 v[16:31], v[242:245], v[2:5], v[16:31]
	ds_read_b128 v[242:245], v143 offset:13888
	v_add_f32_e32 v226, v226, v53
	v_add_f32_e32 v226, v226, v54
	v_add_f32_e32 v226, v226, v55
	v_add_f32_e32 v227, v56, v57
	v_add_f32_e32 v227, v227, v58
	v_add_f32_e32 v227, v227, v59
	v_add_f32_e32 v227, v227, v60
	v_add_f32_e32 v227, v227, v61
	s_waitcnt lgkmcnt(3)
	v_mfma_f32_32x32x16_f16 v[32:47], v[194:197], v[6:9], v[32:47]
	ds_read_b128 v[194:197], v143 offset:9312
	v_add_f32_e32 v227, v227, v62
	v_add_f32_e32 v227, v227, v63
	v_add_f32_e32 v250, v64, v65
	v_add_f32_e32 v250, v250, v66
	v_add_f32_e32 v250, v250, v67
	v_add_f32_e32 v250, v250, v68
	v_add_f32_e32 v250, v250, v69
	v_add_f32_e32 v250, v250, v70
	s_waitcnt lgkmcnt(3)
	v_mfma_f32_32x32x16_f16 v[16:31], v[198:201], v[6:9], v[16:31]
	ds_read_b128 v[198:201], v143 offset:13920
	v_add_f32_e32 v250, v250, v71
	v_add_f32_e32 v251, v72, v73
	v_add_f32_e32 v251, v251, v74
	v_add_f32_e32 v251, v251, v75
	v_add_f32_e32 v251, v251, v76
	v_add_f32_e32 v251, v251, v77
	v_add_f32_e32 v251, v251, v78
	v_add_f32_e32 v251, v251, v79
	s_waitcnt lgkmcnt(3)
	v_mfma_f32_32x32x16_f16 v[32:47], v[238:241], v[10:13], v[32:47]
	v_add_f32_e32 v226, v226, v227
	v_add_f32_e32 v250, v250, v251
	v_add_f32_e32 v226, v226, v250
	v_add_f32_e32 v153, v153, v226
	v_max3_f32 v0, v162, v163, v164
	v_max3_f32 v14, v165, v166, v167
	s_waitcnt lgkmcnt(2)
	v_mfma_f32_32x32x16_f16 v[16:31], v[242:245], v[10:13], v[16:31]
	v_max3_f32 v15, v168, v169, v170
	v_max3_f32 v202, v171, v172, v173
	v_max3_f32 v0, v0, v174, v175
	v_max3_f32 v14, v14, v176, v177
	v_max3_f32 v15, v15, v178, v179
	v_max3_f32 v202, v202, v180, v181
	s_waitcnt lgkmcnt(1)
	v_mfma_f32_32x32x16_f16 v[32:47], v[194:197], v[246:249], v[32:47]
	v_max3_f32 v0, v0, v182, v183
	v_max3_f32 v14, v14, v184, v185
	v_max3_f32 v15, v15, v186, v187
	v_max3_f32 v202, v202, v188, v189
	v_max3_f32 v0, v0, v190, v191
	v_max3_f32 v14, v14, v192, v193
	v_max3_f32 v0, v0, v14, v15
	s_waitcnt lgkmcnt(0)
	v_mfma_f32_32x32x16_f16 v[16:31], v[198:201], v[246:249], v[16:31]
	v_max_f32_e32 v0, v0, v202
	v_mov_b32_e32 v14, v0
	s_nop 1
	v_permlane32_swap_b32_e32 v0, v14
	v_max_f32_e32 v0, v0, v14
	v_cmp_lt_f32_e32 vcc, s79, v0
	s_cbranch_vccnz .Lgq_rare0
.Lgq_cont0:
	s_add_i32 s38, s38, 1
	s_add_i32 s40, s8, -1
	s_cmp_eq_u32 s38, s40
	s_cbranch_scc1 .Lgq_drain1
.Lgq_step1:
	s_waitcnt lgkmcnt(0)
	s_barrier
	ds_read_b128 v[194:197], v141 offset:36864
	ds_read_b128 v[198:201], v141 offset:41472
	ds_read_b128 v[230:233], v141 offset:36896
	ds_read_b128 v[234:237], v141 offset:41504
	v_exp_f32_e32 v162, v162
	v_exp_f32_e32 v163, v163
	v_exp_f32_e32 v164, v164
	v_exp_f32_e32 v165, v165
	s_waitcnt lgkmcnt(3)
	v_mfma_f32_32x32x16_f16 v[48:63], v[194:197], v[80:83], v[204:219]
	ds_read_b128 v[194:197], v141 offset:36928
	v_exp_f32_e32 v166, v166
	v_exp_f32_e32 v167, v167
	v_cvt_pk_f16_f32 v2, v162, v163
	v_exp_f32_e32 v168, v168
	v_exp_f32_e32 v169, v169
	v_cvt_pk_f16_f32 v3, v164, v165
	s_waitcnt lgkmcnt(3)
	v_mfma_f32_32x32x16_f16 v[64:79], v[198:201], v[80:83], v[204:219]
	ds_read_b128 v[198:201], v141 offset:41536
	v_exp_f32_e32 v170, v170
	v_exp_f32_e32 v171, v171
	v_cvt_pk_f16_f32 v4, v166, v167
	v_exp_f32_e32 v172, v172
	v_exp_f32_e32 v173, v173
	v_cvt_pk_f16_f32 v5, v168, v169
	s_waitcnt lgkmcnt(3)
	v_mfma_f32_32x32x16_f16 v[48:63], v[230:233], v[84:87], v[48:63]
	ds_read_b128 v[230:233], v141 offset:36960
	v_exp_f32_e32 v174, v174
	v_exp_f32_e32 v175, v175
	v_cvt_pk_f16_f32 v6, v170, v171
	v_exp_f32_e32 v176, v176
	v_exp_f32_e32 v177, v177
	v_cvt_pk_f16_f32 v7, v172, v173
	s_waitcnt lgkmcnt(3)
	v_mfma_f32_32x32x16_f16 v[64:79], v[234:237], v[84:87], v[64:79]
	ds_read_b128 v[234:237], v141 offset:41568
	v_exp_f32_e32 v178, v178
	v_exp_f32_e32 v179, v179
	v_cvt_pk_f16_f32 v8, v174, v175
	v_exp_f32_e32 v180, v180
	v_exp_f32_e32 v181, v181
	v_cvt_pk_f16_f32 v9, v176, v177
	s_waitcnt lgkmcnt(3)
	v_mfma_f32_32x32x16_f16 v[48:63], v[194:197], v[88:91], v[48:63]
	v_exp_f32_e32 v182, v182
	v_exp_f32_e32 v183, v183
	v_cvt_pk_f16_f32 v10, v178, v179
	v_exp_f32_e32 v184, v184
	v_exp_f32_e32 v185, v185
	v_cvt_pk_f16_f32 v11, v180, v181
	s_waitcnt lgkmcnt(2)
	v_mfma_f32_32x32x16_f16 v[64:79], v[198:201], v[88:91], v[64:79]
	v_exp_f32_e32 v186, v186
	v_exp_f32_e32 v187, v187
	v_cvt_pk_f16_f32 v12, v182, v183
	v_exp_f32_e32 v188, v188
	v_exp_f32_e32 v189, v189
	v_cvt_pk_f16_f32 v13, v184, v185
	s_waitcnt lgkmcnt(1)
	v_mfma_f32_32x32x16_f16 v[48:63], v[230:233], v[92:95], v[48:63]
	v_exp_f32_e32 v190, v190
	v_exp_f32_e32 v191, v191
	v_cvt_pk_f16_f32 v246, v186, v187
	v_exp_f32_e32 v192, v192
	v_exp_f32_e32 v193, v193
	v_cvt_pk_f16_f32 v247, v188, v189
	s_waitcnt lgkmcnt(0)
	v_mfma_f32_32x32x16_f16 v[64:79], v[234:237], v[92:95], v[64:79]
	v_cvt_pk_f16_f32 v248, v190, v191
	v_cvt_pk_f16_f32 v249, v192, v193
	s_add_i32 s40, s38, 2
	s_cmp_ge_u32 s40, s8
	s_cbranch_scc1 .Lgq_nw1
	s_add_i32 s40, s38, 3
	s_cmp_ge_u32 s40, s8
	s_cbranch_scc1 .Lgq_wz1
	s_waitcnt vmcnt(4)
	s_branch .Lgq_ww1

; #define MFMA(a, b, c) __builtin_amdgcn_mfma_f32_32x32x16_f16((a), (b), (c), 0, 0, 0)
; template <int DK, bool MLA>
; DI void attn_item(const h16* __restrict__ Q, const h16* __restrict__ Kp, const h16* __restrict__ Kr, const h16* __restrict__ Vt,
;                   int kbeg, int kend, h16* __restrict__ out, h16* sm) {
;     ...
;       *(u32x4*)(ksm + key * KS + part * 8) = RK[i];
;     }
; #pragma unroll
;     for (int i = 0; i < 2; ++i) {
;       const int c = tid + 256 * i, dv = c >> 3, kc = c & 7;
;       *(u32x4*)(vsm + dv * 72 + kc * 8) = RV[i];
;     }
;     __syncthreads();
;     if (it + 2 < ntile) ATT_GLOAD(RK, RV, kbeg + (it + 2) * 64)
;     f32x16 st[2];
;     const float negm = -m;
; #pragma unroll
;     for (int i = 0; i < 16; ++i) { st[0][i] = negm; st[1][i] = negm; }
; #pragma unroll
;     for (int ks = 0; ks < DK / 16; ++ks) {
;       h16x8 k0 = *(const h16x8*)(ksm + r * KS + ks * 16 + hh * 8);
;       h16x8 k1 = *(const h16x8*)(ksm + (32 + r) * KS + ks * 16 + hh * 8);
;       st[0] = MFMA(k0, qf[ks], st[0]);
;       st[1] = MFMA(k1, qf[ks], st[1]);
;     }
;     float mx = fmaxf(st[0][0], st[1][0]);
; #pragma unroll
;     for (int i = 1; i < 16; ++i) mx = fmaxf(mx, fmaxf(st[0][i], st[1][i]));
;     mx = x32_max(mx);
;     if (__builtin_amdgcn_ballot_w64(mx > 8.f) != 0) {
;       const float dlt = fmaxf(mx, 0.f);
;       const float alpha = __builtin_amdgcn_exp2f(-dlt);
;       m += dlt;
;       lsum *= alpha;
; #pragma unroll
;       for (int i = 0; i < 16; ++i) { ot[0][i] *= alpha; ot[1][i] *= alpha; st[0][i] -= dlt; st[1][i] -= dlt; }
;     }
;     float ps = 0.f;
; #pragma unroll
;     for (int i = 0; i < 16; ++i) {
;       st[0][i] = __builtin_amdgcn_exp2f(st[0][i]);
;       st[1][i] = __builtin_amdgcn_exp2f(st[1][i]);
;       ps += st[0][i] + st[1][i];
;     }
;     lsum += ps;
; #pragma unroll
;     for (int s4 = 0; s4 < 4; ++s4) {
;       const int kt2 = s4 >> 1, hf = s4 & 1;
;       h16x8 pb;
; #pragma unroll
;       for (int j = 0; j < 8; ++j) pb[j] = (h16)st[kt2][8 * hf + j];
;       const int kb = kt2 * 32 + 16 * hf;
; #pragma unroll
;       for (int dt = 0; dt < 2; ++dt) {
;         const h16* vp = vsm + (dt * 32 + r) * 72 + kb + 4 * hh;
;         h16x4 lo = *(const h16x4*)vp, hi = *(const h16x4*)(vp + 8);
;         h16x8 va = __builtin_shufflevector(lo, hi, 0, 1, 2, 3, 4, 5, 6, 7);
;         ot[dt] = MFMA(va, pb, ot[dt]);
;       }
.Lgq_ww1:
	ds_write_b128 v129, v[100:103] offset:0
	ds_write_b128 v131, v[96:99] offset:0
	ds_write_b128 v140, v[108:111] offset:9216
	ds_write_b128 v142, v[104:107] offset:9216
.Lgq_nw1:
	ds_read_b128 v[238:241], v143 offset:27648
	ds_read_b128 v[242:245], v143 offset:32256
	ds_read_b128 v[194:197], v143 offset:27680
	ds_read_b128 v[198:201], v143 offset:32288
	s_waitcnt lgkmcnt(3)
	v_mfma_f32_32x32x16_f16 v[32:47], v[238:241], v[2:5], v[32:47]
	ds_read_b128 v[238:241], v143 offset:27712
	s_add_i32 s40, s38, 4
	s_cmp_ge_u32 s40, s8
	s_cbranch_scc1 .Lgq_nl1
	s_lshl_b32 s40, s40, 7
	s_mov_b32 s41, 0
	global_load_dwordx4 v[100:103], v[220:221], off
	global_load_dwordx4 v[96:99], v[222:223], off
	v_lshl_add_u64 v[14:15], v[134:135], 0, s[40:41]
	v_lshl_add_u64 v[250:251], v[132:133], 0, s[40:41]
	global_load_dwordx4 v[108:111], v[14:15], off
	global_load_dwordx4 v[104:107], v[250:251], off
	v_lshl_add_u64 v[220:221], v[220:221], 0, v[228:229]
	v_lshl_add_u64 v[222:223], v[222:223], 0, v[228:229]
.Lgq_nl1:
	v_add_f32_e32 v226, v162, v163
	v_add_f32_e32 v226, v226, v164
	v_add_f32_e32 v226, v226, v165
	v_add_f32_e32 v226, v226, v166
	s_waitcnt lgkmcnt(3)
	v_mfma_f32_32x32x16_f16 v[16:31], v[242:245], v[2:5], v[16:31]
	ds_read_b128 v[242:245], v143 offset:32320
	v_add_f32_e32 v226, v226, v167
	v_add_f32_e32 v226, v226, v168
	v_add_f32_e32 v226, v226, v169
	v_add_f32_e32 v227, v170, v171
	v_add_f32_e32 v227, v227, v172
	v_add_f32_e32 v227, v227, v173
	v_add_f32_e32 v227, v227, v174
	v_add_f32_e32 v227, v227, v175
	s_waitcnt lgkmcnt(3)
	v_mfma_f32_32x32x16_f16 v[32:47], v[194:197], v[6:9], v[32:47]
	ds_read_b128 v[194:197], v143 offset:27744
	v_add_f32_e32 v227, v227, v176
	v_add_f32_e32 v227, v227, v177
	v_add_f32_e32 v250, v178, v179
	v_add_f32_e32 v250, v250, v180
	v_add_f32_e32 v250, v250, v181
	v_add_f32_e32 v250, v250, v182
	v_add_f32_e32 v250, v250, v183
	v_add_f32_e32 v250, v250, v184
	s_waitcnt lgkmcnt(3)
	v_mfma_f32_32x32x16_f16 v[16:31], v[198:201], v[6:9], v[16:31]
	ds_read_b128 v[198:201], v143 offset:32352
	v_add_f32_e32 v250, v250, v185
	v_add_f32_e32 v251, v186, v187
	v_add_f32_e32 v251, v251, v188
	v_add_f32_e32 v251, v251, v189
	v_add_f32_e32 v251, v251, v190
	v_add_f32_e32 v251, v251, v191
	v_add_f32_e32 v251, v251, v192
	v_add_f32_e32 v251, v251, v193
	s_waitcnt lgkmcnt(3)
	v_mfma_f32_32x32x16_f16 v[32:47], v[238:241], v[10:13], v[32:47]
	v_add_f32_e32 v226, v226, v227
	v_add_f32_e32 v250, v250, v251
	v_add_f32_e32 v226, v226, v250
	v_add_f32_e32 v153, v153, v226
	v_max3_f32 v0, v48, v49, v50
	v_max3_f32 v14, v51, v52, v53
	s_waitcnt lgkmcnt(2)
	v_mfma_f32_32x32x16_f16 v[16:31], v[242:245], v[10:13], v[16:31]
	v_max3_f32 v15, v54, v55, v56
	v_max3_f32 v202, v57, v58, v59
	v_max3_f32 v0, v0, v60, v61
	v_max3_f32 v14, v14, v62, v63
	v_max3_f32 v15, v15, v64, v65
	v_max3_f32 v202, v202, v66, v67
	s_waitcnt lgkmcnt(1)
	v_mfma_f32_32x32x16_f16 v[32:47], v[194:197], v[246:249], v[32:47]
	v_max3_f32 v0, v0, v68, v69
	v_max3_f32 v14, v14, v70, v71
	v_max3_f32 v15, v15, v72, v73
	v_max3_f32 v202, v202, v74, v75
	v_max3_f32 v0, v0, v76, v77
	v_max3_f32 v14, v14, v78, v79
	v_max3_f32 v0, v0, v14, v15
	s_waitcnt lgkmcnt(0)
	v_mfma_f32_32x32x16_f16 v[16:31], v[198:201], v[246:249], v[16:31]
	v_max_f32_e32 v0, v0, v202
	v_mov_b32_e32 v14, v0
	s_nop 1
	v_permlane32_swap_b32_e32 v0, v14
	v_max_f32_e32 v0, v0, v14
	v_cmp_lt_f32_e32 vcc, s79, v0
	s_cbranch_vccnz .Lgq_rare1
.Lgq_cont1:
	s_add_i32 s38, s38, 1
.Lgq_step2:
	s_waitcnt lgkmcnt(0)
	s_barrier
	ds_read_b128 v[194:197], v141 offset:0
	ds_read_b128 v[198:201], v141 offset:4608
	ds_read_b128 v[230:233], v141 offset:32
	ds_read_b128 v[234:237], v141 offset:4640
	v_exp_f32_e32 v48, v48
	v_exp_f32_e32 v49, v49
	v_exp_f32_e32 v50, v50
	v_exp_f32_e32 v51, v51
	s_waitcnt lgkmcnt(3)
	v_mfma_f32_32x32x16_f16 v[162:177], v[194:197], v[80:83], v[204:219]
	ds_read_b128 v[194:197], v141 offset:64
	v_exp_f32_e32 v52, v52
	v_exp_f32_e32 v53, v53
	v_cvt_pk_f16_f32 v2, v48, v49
	v_exp_f32_e32 v54, v54
	v_exp_f32_e32 v55, v55
	v_cvt_pk_f16_f32 v3, v50, v51
	s_waitcnt lgkmcnt(3)
	v_mfma_f32_32x32x16_f16 v[178:193], v[198:201], v[80:83], v[204:219]
	ds_read_b128 v[198:201], v141 offset:4672
	v_exp_f32_e32 v56, v56
	v_exp_f32_e32 v57, v57
	v_cvt_pk_f16_f32 v4, v52, v53
	v_exp_f32_e32 v58, v58
	v_exp_f32_e32 v59, v59
	v_cvt_pk_f16_f32 v5, v54, v55
	s_waitcnt lgkmcnt(3)
	v_mfma_f32_32x32x16_f16 v[162:177], v[230:233], v[84:87], v[162:177]
	ds_read_b128 v[230:233], v141 offset:96
	v_exp_f32_e32 v60, v60
	v_exp_f32_e32 v61, v61
	v_cvt_pk_f16_f32 v6, v56, v57
	v_exp_f32_e32 v62, v62
	v_exp_f32_e32 v63, v63
	v_cvt_pk_f16_f32 v7, v58, v59
	s_waitcnt lgkmcnt(3)
	v_mfma_f32_32x32x16_f16 v[178:193], v[234:237], v[84:87], v[178:193]
	ds_read_b128 v[234:237], v141 offset:4704
	v_exp_f32_e32 v64, v64
	v_exp_f32_e32 v65, v65
	v_cvt_pk_f16_f32 v8, v60, v61
	v_exp_f32_e32 v66, v66
	v_exp_f32_e32 v67, v67
	v_cvt_pk_f16_f32 v9, v62, v63
	s_waitcnt lgkmcnt(3)
	v_mfma_f32_32x32x16_f16 v[162:177], v[194:197], v[88:91], v[162:177]
	v_exp_f32_e32 v68, v68
	v_exp_f32_e32 v69, v69
	v_cvt_pk_f16_f32 v10, v64, v65
	v_exp_f32_e32 v70, v70
	v_exp_f32_e32 v71, v71
	v_cvt_pk_f16_f32 v11, v66, v67
	s_waitcnt lgkmcnt(2)
	v_mfma_f32_32x32x16_f16 v[178:193], v[198:201], v[88:91], v[178:193]
	v_exp_f32_e32 v72, v72
	v_exp_f32_e32 v73, v73
	v_cvt_pk_f16_f32 v12, v68, v69
	v_exp_f32_e32 v74, v74
	v_exp_f32_e32 v75, v75
	v_cvt_pk_f16_f32 v13, v70, v71
	s_waitcnt lgkmcnt(1)
	v_mfma_f32_32x32x16_f16 v[162:177], v[230:233], v[92:95], v[162:177]
	v_exp_f32_e32 v76, v76
	v_exp_f32_e32 v77, v77
	v_cvt_pk_f16_f32 v246, v72, v73
	v_exp_f32_e32 v78, v78
	v_exp_f32_e32 v79, v79
	v_cvt_pk_f16_f32 v247, v74, v75
	s_waitcnt lgkmcnt(0)
	v_mfma_f32_32x32x16_f16 v[178:193], v[234:237], v[92:95], v[178:193]
	v_cvt_pk_f16_f32 v248, v76, v77
	v_cvt_pk_f16_f32 v249, v78, v79
	s_add_i32 s40, s38, 2
	s_cmp_ge_u32 s40, s8
	s_cbranch_scc1 .Lgq_nw2
	s_add_i32 s40, s38, 3
	s_cmp_ge_u32 s40, s8
	s_cbranch_scc1 .Lgq_wz2
	s_waitcnt vmcnt(4)
	s_branch .Lgq_ww2

; #define MFMA(a, b, c) __builtin_amdgcn_mfma_f32_32x32x16_f16((a), (b), (c), 0, 0, 0)
; template <int DK, bool MLA>
; DI void attn_item(const h16* __restrict__ Q, const h16* __restrict__ Kp, const h16* __restrict__ Kr, const h16* __restrict__ Vt,
;                   int kbeg, int kend, h16* __restrict__ out, h16* sm) {
;     ...
;       *(u32x4*)(ksm + key * KS + part * 8) = RK[i];
;     }
; #pragma unroll
;     for (int i = 0; i < 2; ++i) {
;       const int c = tid + 256 * i, dv = c >> 3, kc = c & 7;
;       *(u32x4*)(vsm + dv * 72 + kc * 8) = RV[i];
;     }
;     __syncthreads();
;     if (it + 2 < ntile) ATT_GLOAD(RK, RV, kbeg + (it + 2) * 64)
;     f32x16 st[2];
;     const float negm = -m;
; #pragma unroll
;     for (int i = 0; i < 16; ++i) { st[0][i] = negm; st[1][i] = negm; }
; #pragma unroll
;     for (int ks = 0; ks < DK / 16; ++ks) {
;       h16x8 k0 = *(const h16x8*)(ksm + r * KS + ks * 16 + hh * 8);
;       h16x8 k1 = *(const h16x8*)(ksm + (32 + r) * KS + ks * 16 + hh * 8);
;       st[0] = MFMA(k0, qf[ks], st[0]);
;       st[1] = MFMA(k1, qf[ks], st[1]);
;     }
;     float mx = fmaxf(st[0][0], st[1][0]);
; #pragma unroll
;     for (int i = 1; i < 16; ++i) mx = fmaxf(mx, fmaxf(st[0][i], st[1][i]));
;     mx = x32_max(mx);
;     if (__builtin_amdgcn_ballot_w64(mx > 8.f) != 0) {
;       const float dlt = fmaxf(mx, 0.f);
;       const float alpha = __builtin_amdgcn_exp2f(-dlt);
;       m += dlt;
;       lsum *= alpha;
; #pragma unroll
;       for (int i = 0; i < 16; ++i) { ot[0][i] *= alpha; ot[1][i] *= alpha; st[0][i] -= dlt; st[1][i] -= dlt; }
;     }
;     float ps = 0.f;
; #pragma unroll
;     for (int i = 0; i < 16; ++i) {
;       st[0][i] = __builtin_amdgcn_exp2f(st[0][i]);
;       st[1][i] = __builtin_amdgcn_exp2f(st[1][i]);
;       ps += st[0][i] + st[1][i];
;     }
;     lsum += ps;
; #pragma unroll
;     for (int s4 = 0; s4 < 4; ++s4) {
;       const int kt2 = s4 >> 1, hf = s4 & 1;
;       h16x8 pb;
; #pragma unroll
;       for (int j = 0; j < 8; ++j) pb[j] = (h16)st[kt2][8 * hf + j];
;       const int kb = kt2 * 32 + 16 * hf;
; #pragma unroll
;       for (int dt = 0; dt < 2; ++dt) {
;         const h16* vp = vsm + (dt * 32 + r) * 72 + kb + 4 * hh;
;         h16x4 lo = *(const h16x4*)vp, hi = *(const h16x4*)(vp + 8);
;         h16x8 va = __builtin_shufflevector(lo, hi, 0, 1, 2, 3, 4, 5, 6, 7);
;         ot[dt] = MFMA(va, pb, ot[dt]);
;       }
.Lgq_ww2:
	ds_write_b128 v129, v[124:127] offset:18432
	ds_write_b128 v131, v[120:123] offset:18432
	ds_write_b128 v140, v[116:119] offset:27648
	ds_write_b128 v142, v[112:115] offset:27648
.Lgq_nw2:
	ds_read_b128 v[238:241], v143 offset:46080
	ds_read_b128 v[242:245], v143 offset:50688
	ds_read_b128 v[194:197], v143 offset:46112
	ds_read_b128 v[198:201], v143 offset:50720
	s_waitcnt lgkmcnt(3)
	v_mfma_f32_32x32x16_f16 v[32:47], v[238:241], v[2:5], v[32:47]
	ds_read_b128 v[238:241], v143 offset:46144
	s_add_i32 s40, s38, 4
	s_cmp_ge_u32 s40, s8
	s_cbranch_scc1 .Lgq_nl2
	s_lshl_b32 s40, s40, 7
	s_mov_b32 s41, 0
	global_load_dwordx4 v[124:127], v[220:221], off
	global_load_dwordx4 v[120:123], v[222:223], off
	v_lshl_add_u64 v[14:15], v[138:139], 0, s[40:41]
	v_lshl_add_u64 v[250:251], v[136:137], 0, s[40:41]
	global_load_dwordx4 v[116:119], v[14:15], off
	global_load_dwordx4 v[112:115], v[250:251], off
	v_lshl_add_u64 v[220:221], v[220:221], 0, v[228:229]
	v_lshl_add_u64 v[222:223], v[222:223], 0, v[228:229]
.Lgq_nl2:
	v_add_f32_e32 v226, v48, v49
	v_add_f32_e32 v226, v226, v50
	v_add_f32_e32 v226, v226, v51
	v_add_f32_e32 v226, v226, v52
	s_waitcnt lgkmcnt(3)
	v_mfma_f32_32x32x16_f16 v[16:31], v[242:245], v[2:5], v[16:31]
	ds_read_b128 v[242:245], v143 offset:50752
	v_add_f32_e32 v226, v226, v53
	v_add_f32_e32 v226, v226, v54
	v_add_f32_e32 v226, v226, v55
	v_add_f32_e32 v227, v56, v57
	v_add_f32_e32 v227, v227, v58
	v_add_f32_e32 v227, v227, v59
	v_add_f32_e32 v227, v227, v60
	v_add_f32_e32 v227, v227, v61
	s_waitcnt lgkmcnt(3)
	v_mfma_f32_32x32x16_f16 v[32:47], v[194:197], v[6:9], v[32:47]
	ds_read_b128 v[194:197], v143 offset:46176
	v_add_f32_e32 v227, v227, v62
	v_add_f32_e32 v227, v227, v63
	v_add_f32_e32 v250, v64, v65
	v_add_f32_e32 v250, v250, v66
	v_add_f32_e32 v250, v250, v67
	v_add_f32_e32 v250, v250, v68
	v_add_f32_e32 v250, v250, v69
	v_add_f32_e32 v250, v250, v70
	s_waitcnt lgkmcnt(3)
	v_mfma_f32_32x32x16_f16 v[16:31], v[198:201], v[6:9], v[16:31]
	ds_read_b128 v[198:201], v143 offset:50784
	v_add_f32_e32 v250, v250, v71
	v_add_f32_e32 v251, v72, v73
	v_add_f32_e32 v251, v251, v74
	v_add_f32_e32 v251, v251, v75
	v_add_f32_e32 v251, v251, v76
	v_add_f32_e32 v251, v251, v77
	v_add_f32_e32 v251, v251, v78
	v_add_f32_e32 v251, v251, v79
	s_waitcnt lgkmcnt(3)
	v_mfma_f32_32x32x16_f16 v[32:47], v[238:241], v[10:13], v[32:47]
	v_add_f32_e32 v226, v226, v227
	v_add_f32_e32 v250, v250, v251
	v_add_f32_e32 v226, v226, v250
	v_add_f32_e32 v153, v153, v226
	v_max3_f32 v0, v162, v163, v164
	v_max3_f32 v14, v165, v166, v167
	s_waitcnt lgkmcnt(2)
	v_mfma_f32_32x32x16_f16 v[16:31], v[242:245], v[10:13], v[16:31]
	v_max3_f32 v15, v168, v169, v170
	v_max3_f32 v202, v171, v172, v173
	v_max3_f32 v0, v0, v174, v175
	v_max3_f32 v14, v14, v176, v177
	v_max3_f32 v15, v15, v178, v179
	v_max3_f32 v202, v202, v180, v181
	s_waitcnt lgkmcnt(1)
	v_mfma_f32_32x32x16_f16 v[32:47], v[194:197], v[246:249], v[32:47]
	v_max3_f32 v0, v0, v182, v183
	v_max3_f32 v14, v14, v184, v185
	v_max3_f32 v15, v15, v186, v187
	v_max3_f32 v202, v202, v188, v189
	v_max3_f32 v0, v0, v190, v191
	v_max3_f32 v14, v14, v192, v193
	v_max3_f32 v0, v0, v14, v15
	s_waitcnt lgkmcnt(0)
	v_mfma_f32_32x32x16_f16 v[16:31], v[198:201], v[246:249], v[16:31]
	v_max_f32_e32 v0, v0, v202
	v_mov_b32_e32 v14, v0
	s_nop 1
	v_permlane32_swap_b32_e32 v0, v14
	v_max_f32_e32 v0, v0, v14
	v_cmp_lt_f32_e32 vcc, s79, v0
	s_cbranch_vccnz .Lgq_rare2

; #define MFMA(a, b, c) __builtin_amdgcn_mfma_f32_32x32x16_f16((a), (b), (c), 0, 0, 0)
; template <int DK, bool MLA>
; DI void attn_item(const h16* __restrict__ Q, const h16* __restrict__ Kp, const h16* __restrict__ Kr, const h16* __restrict__ Vt,
;                   int kbeg, int kend, h16* __restrict__ out, h16* sm) {
;     ...
;     f32x16 st[2];
;     const float negm = -m;
; #pragma unroll
;     for (int i = 0; i < 16; ++i) { st[0][i] = negm; st[1][i] = negm; }
; #pragma unroll
;     for (int ks = 0; ks < DK / 16; ++ks) {
;       h16x8 k0 = *(const h16x8*)(ksm + r * KS + ks * 16 + hh * 8);
;       h16x8 k1 = *(const h16x8*)(ksm + (32 + r) * KS + ks * 16 + hh * 8);
;       st[0] = MFMA(k0, qf[ks], st[0]);
;       st[1] = MFMA(k1, qf[ks], st[1]);
;     }
;     float mx = fmaxf(st[0][0], st[1][0]);
; #pragma unroll
;     for (int i = 1; i < 16; ++i) mx = fmaxf(mx, fmaxf(st[0][i], st[1][i]));
;     mx = x32_max(mx);
;     if (__builtin_amdgcn_ballot_w64(mx > 8.f) != 0) {
;       const float dlt = fmaxf(mx, 0.f);
;       const float alpha = __builtin_amdgcn_exp2f(-dlt);
;       m += dlt;
;       lsum *= alpha;
; #pragma unroll
;       for (int i = 0; i < 16; ++i) { ot[0][i] *= alpha; ot[1][i] *= alpha; st[0][i] -= dlt; st[1][i] -= dlt; }
;     }
;     float ps = 0.f;
; #pragma unroll
;     for (int i = 0; i < 16; ++i) {
;       st[0][i] = __builtin_amdgcn_exp2f(st[0][i]);
;       st[1][i] = __builtin_amdgcn_exp2f(st[1][i]);
;       ps += st[0][i] + st[1][i];
;     }
;     lsum += ps;
; #pragma unroll
;     for (int s4 = 0; s4 < 4; ++s4) {
;       const int kt2 = s4 >> 1, hf = s4 & 1;
;       h16x8 pb;
; #pragma unroll
;       for (int j = 0; j < 8; ++j) pb[j] = (h16)st[kt2][8 * hf + j];
.Lgq_step3:
	s_waitcnt lgkmcnt(0)
	s_barrier
	ds_read_b128 v[194:197], v141 offset:18432
	ds_read_b128 v[198:201], v141 offset:23040
	ds_read_b128 v[230:233], v141 offset:18464
	ds_read_b128 v[234:237], v141 offset:23072
	v_exp_f32_e32 v162, v162
	v_exp_f32_e32 v163, v163
	v_exp_f32_e32 v164, v164
	v_exp_f32_e32 v165, v165
	s_waitcnt lgkmcnt(3)
	v_mfma_f32_32x32x16_f16 v[48:63], v[194:197], v[80:83], v[204:219]
	ds_read_b128 v[194:197], v141 offset:18496
	v_exp_f32_e32 v166, v166
	v_exp_f32_e32 v167, v167
	v_cvt_pk_f16_f32 v2, v162, v163
	v_exp_f32_e32 v168, v168
	v_exp_f32_e32 v169, v169
	v_cvt_pk_f16_f32 v3, v164, v165
	s_waitcnt lgkmcnt(3)
	v_mfma_f32_32x32x16_f16 v[64:79], v[198:201], v[80:83], v[204:219]
	ds_read_b128 v[198:201], v141 offset:23104
	v_exp_f32_e32 v170, v170
	v_exp_f32_e32 v171, v171
	v_cvt_pk_f16_f32 v4, v166, v167
	v_exp_f32_e32 v172, v172
	v_exp_f32_e32 v173, v173
	v_cvt_pk_f16_f32 v5, v168, v169
	s_waitcnt lgkmcnt(3)
	v_mfma_f32_32x32x16_f16 v[48:63], v[230:233], v[84:87], v[48:63]
	ds_read_b128 v[230:233], v141 offset:18528
	v_exp_f32_e32 v174, v174
	v_exp_f32_e32 v175, v175
	v_cvt_pk_f16_f32 v6, v170, v171
	v_exp_f32_e32 v176, v176
	v_exp_f32_e32 v177, v177
	v_cvt_pk_f16_f32 v7, v172, v173
	s_waitcnt lgkmcnt(3)
	v_mfma_f32_32x32x16_f16 v[64:79], v[234:237], v[84:87], v[64:79]
	ds_read_b128 v[234:237], v141 offset:23136
	v_exp_f32_e32 v178, v178
	v_exp_f32_e32 v179, v179
	v_cvt_pk_f16_f32 v8, v174, v175
	v_exp_f32_e32 v180, v180
	v_exp_f32_e32 v181, v181
	v_cvt_pk_f16_f32 v9, v176, v177
	s_waitcnt lgkmcnt(3)
	v_mfma_f32_32x32x16_f16 v[48:63], v[194:197], v[88:91], v[48:63]
	v_exp_f32_e32 v182, v182
	v_exp_f32_e32 v183, v183
	v_cvt_pk_f16_f32 v10, v178, v179
	v_exp_f32_e32 v184, v184
	v_exp_f32_e32 v185, v185
	v_cvt_pk_f16_f32 v11, v180, v181
	s_waitcnt lgkmcnt(2)
	v_mfma_f32_32x32x16_f16 v[64:79], v[198:201], v[88:91], v[64:79]
	v_exp_f32_e32 v186, v186
	v_exp_f32_e32 v187, v187
	v_cvt_pk_f16_f32 v12, v182, v183
	v_exp_f32_e32 v188, v188
	v_exp_f32_e32 v189, v189
	v_cvt_pk_f16_f32 v13, v184, v185
	s_waitcnt lgkmcnt(1)
	v_mfma_f32_32x32x16_f16 v[48:63], v[230:233], v[92:95], v[48:63]
	v_exp_f32_e32 v190, v190
	v_exp_f32_e32 v191, v191
	v_cvt_pk_f16_f32 v246, v186, v187
	v_exp_f32_e32 v192, v192
	v_exp_f32_e32 v193, v193
	v_cvt_pk_f16_f32 v247, v188, v189
	s_waitcnt lgkmcnt(0)
	v_mfma_f32_32x32x16_f16 v[64:79], v[234:237], v[92:95], v[64:79]
	v_cvt_pk_f16_f32 v248, v190, v191
	v_cvt_pk_f16_f32 v249, v192, v193
	s_add_i32 s40, s38, 2
	s_cmp_ge_u32 s40, s8
	s_cbranch_scc1 .Lgq_nw3
	s_add_i32 s40, s38, 3
	s_cmp_ge_u32 s40, s8
	s_cbranch_scc1 .Lgq_wz3
	s_waitcnt vmcnt(4)
	s_branch .Lgq_ww3

; #define MFMA(a, b, c) __builtin_amdgcn_mfma_f32_32x32x16_f16((a), (b), (c), 0, 0, 0)
; template <int DK, bool MLA>
; DI void attn_item(const h16* __restrict__ Q, const h16* __restrict__ Kp, const h16* __restrict__ Kr, const h16* __restrict__ Vt,
;                   int kbeg, int kend, h16* __restrict__ out, h16* sm) {
;     ...
;       *(u32x4*)(ksm + key * KS + part * 8) = RK[i];
;     }
; #pragma unroll
;     for (int i = 0; i < 2; ++i) {
;       const int c = tid + 256 * i, dv = c >> 3, kc = c & 7;
;       *(u32x4*)(vsm + dv * 72 + kc * 8) = RV[i];
;     }
;     __syncthreads();
;     if (it + 2 < ntile) ATT_GLOAD(RK, RV, kbeg + (it + 2) * 64)
;     f32x16 st[2];
;     const float negm = -m;
; #pragma unroll
;     for (int i = 0; i < 16; ++i) { st[0][i] = negm; st[1][i] = negm; }
; #pragma unroll
;     for (int ks = 0; ks < DK / 16; ++ks) {
;       h16x8 k0 = *(const h16x8*)(ksm + r * KS + ks * 16 + hh * 8);
;       h16x8 k1 = *(const h16x8*)(ksm + (32 + r) * KS + ks * 16 + hh * 8);
;       st[0] = MFMA(k0, qf[ks], st[0]);
;       st[1] = MFMA(k1, qf[ks], st[1]);
;     }
;     float mx = fmaxf(st[0][0], st[1][0]);
; #pragma unroll
;     for (int i = 1; i < 16; ++i) mx = fmaxf(mx, fmaxf(st[0][i], st[1][i]));
;     mx = x32_max(mx);
;     if (__builtin_amdgcn_ballot_w64(mx > 8.f) != 0) {
;       const float dlt = fmaxf(mx, 0.f);
;       const float alpha = __builtin_amdgcn_exp2f(-dlt);
;       m += dlt;
;       lsum *= alpha;
; #pragma unroll
;       for (int i = 0; i < 16; ++i) { ot[0][i] *= alpha; ot[1][i] *= alpha; st[0][i] -= dlt; st[1][i] -= dlt; }
;     }
;     float ps = 0.f;
; #pragma unroll
;     for (int i = 0; i < 16; ++i) {
;       st[0][i] = __builtin_amdgcn_exp2f(st[0][i]);
;       st[1][i] = __builtin_amdgcn_exp2f(st[1][i]);
;       ps += st[0][i] + st[1][i];
;     }
;     lsum += ps;
; #pragma unroll
;     for (int s4 = 0; s4 < 4; ++s4) {
;       const int kt2 = s4 >> 1, hf = s4 & 1;
;       h16x8 pb;
; #pragma unroll
;       for (int j = 0; j < 8; ++j) pb[j] = (h16)st[kt2][8 * hf + j];
;       const int kb = kt2 * 32 + 16 * hf;
; #pragma unroll
;       for (int dt = 0; dt < 2; ++dt) {
;         const h16* vp = vsm + (dt * 32 + r) * 72 + kb + 4 * hh;
;         h16x4 lo = *(const h16x4*)vp, hi = *(const h16x4*)(vp + 8);
;         h16x8 va = __builtin_shufflevector(lo, hi, 0, 1, 2, 3, 4, 5, 6, 7);
;         ot[dt] = MFMA(va, pb, ot[dt]);
;       }
.Lgq_ww3:
	ds_write_b128 v129, v[100:103] offset:36864
	ds_write_b128 v131, v[96:99] offset:36864
	ds_write_b128 v140, v[108:111] offset:46080
	ds_write_b128 v142, v[104:107] offset:46080
.Lgq_nw3:
	ds_read_b128 v[238:241], v143 offset:9216
	ds_read_b128 v[242:245], v143 offset:13824
	ds_read_b128 v[194:197], v143 offset:9248
	ds_read_b128 v[198:201], v143 offset:13856
	s_waitcnt lgkmcnt(3)
	v_mfma_f32_32x32x16_f16 v[32:47], v[238:241], v[2:5], v[32:47]
	ds_read_b128 v[238:241], v143 offset:9280
	s_add_i32 s40, s38, 4
	s_cmp_ge_u32 s40, s8
	s_cbranch_scc1 .Lgq_nl3
	s_lshl_b32 s40, s40, 7
	s_mov_b32 s41, 0
	global_load_dwordx4 v[100:103], v[220:221], off
	global_load_dwordx4 v[96:99], v[222:223], off
	v_lshl_add_u64 v[14:15], v[134:135], 0, s[40:41]
	v_lshl_add_u64 v[250:251], v[132:133], 0, s[40:41]
	global_load_dwordx4 v[108:111], v[14:15], off
	global_load_dwordx4 v[104:107], v[250:251], off
	v_lshl_add_u64 v[220:221], v[220:221], 0, v[228:229]
	v_lshl_add_u64 v[222:223], v[222:223], 0, v[228:229]
.Lgq_nl3:
	v_add_f32_e32 v226, v162, v163
	v_add_f32_e32 v226, v226, v164
	v_add_f32_e32 v226, v226, v165
	v_add_f32_e32 v226, v226, v166
	s_waitcnt lgkmcnt(3)
	v_mfma_f32_32x32x16_f16 v[16:31], v[242:245], v[2:5], v[16:31]
	ds_read_b128 v[242:245], v143 offset:13888
	v_add_f32_e32 v226, v226, v167
	v_add_f32_e32 v226, v226, v168
	v_add_f32_e32 v226, v226, v169
	v_add_f32_e32 v227, v170, v171
	v_add_f32_e32 v227, v227, v172
	v_add_f32_e32 v227, v227, v173
	v_add_f32_e32 v227, v227, v174
	v_add_f32_e32 v227, v227, v175
	s_waitcnt lgkmcnt(3)
	v_mfma_f32_32x32x16_f16 v[32:47], v[194:197], v[6:9], v[32:47]
	ds_read_b128 v[194:197], v143 offset:9312
	v_add_f32_e32 v227, v227, v176
	v_add_f32_e32 v227, v227, v177
	v_add_f32_e32 v250, v178, v179
	v_add_f32_e32 v250, v250, v180
	v_add_f32_e32 v250, v250, v181
	v_add_f32_e32 v250, v250, v182
	v_add_f32_e32 v250, v250, v183
	v_add_f32_e32 v250, v250, v184
	s_waitcnt lgkmcnt(3)
	v_mfma_f32_32x32x16_f16 v[16:31], v[198:201], v[6:9], v[16:31]
	ds_read_b128 v[198:201], v143 offset:13920
	v_add_f32_e32 v250, v250, v185
	v_add_f32_e32 v251, v186, v187
	v_add_f32_e32 v251, v251, v188
	v_add_f32_e32 v251, v251, v189
	v_add_f32_e32 v251, v251, v190
	v_add_f32_e32 v251, v251, v191
	v_add_f32_e32 v251, v251, v192
	v_add_f32_e32 v251, v251, v193
	s_waitcnt lgkmcnt(3)
	v_mfma_f32_32x32x16_f16 v[32:47], v[238:241], v[10:13], v[32:47]
	v_add_f32_e32 v226, v226, v227
	v_add_f32_e32 v250, v250, v251
	v_add_f32_e32 v226, v226, v250
	v_add_f32_e32 v153, v153, v226
	v_max3_f32 v0, v48, v49, v50
	v_max3_f32 v14, v51, v52, v53
	s_waitcnt lgkmcnt(2)
	v_mfma_f32_32x32x16_f16 v[16:31], v[242:245], v[10:13], v[16:31]
	v_max3_f32 v15, v54, v55, v56
	v_max3_f32 v202, v57, v58, v59
	v_max3_f32 v0, v0, v60, v61
	v_max3_f32 v14, v14, v62, v63
	v_max3_f32 v15, v15, v64, v65
	v_max3_f32 v202, v202, v66, v67
	s_waitcnt lgkmcnt(1)
	v_mfma_f32_32x32x16_f16 v[32:47], v[194:197], v[246:249], v[32:47]
	v_max3_f32 v0, v0, v68, v69
	v_max3_f32 v14, v14, v70, v71
	v_max3_f32 v15, v15, v72, v73
	v_max3_f32 v202, v202, v74, v75
	v_max3_f32 v0, v0, v76, v77
	v_max3_f32 v14, v14, v78, v79
	v_max3_f32 v0, v0, v14, v15
	s_waitcnt lgkmcnt(0)
	v_mfma_f32_32x32x16_f16 v[16:31], v[198:201], v[246:249], v[16:31]
	v_max_f32_e32 v0, v0, v202
	v_mov_b32_e32 v14, v0
	s_nop 1
	v_permlane32_swap_b32_e32 v0, v14
	v_max_f32_e32 v0, v0, v14
	v_cmp_lt_f32_e32 vcc, s79, v0
	s_cbranch_vccnz .Lgq_rare3

; #define MFMA(a, b, c) __builtin_amdgcn_mfma_f32_32x32x16_f16((a), (b), (c), 0, 0, 0)
; template <int DK, bool MLA>
; DI void attn_item(const h16* __restrict__ Q, const h16* __restrict__ Kp, const h16* __restrict__ Kr, const h16* __restrict__ Vt,
;                   int kbeg, int kend, h16* __restrict__ out, h16* sm) {
;     ...
;     f32x16 st[2];
;     const float negm = -m;
; #pragma unroll
;     for (int i = 0; i < 16; ++i) { st[0][i] = negm; st[1][i] = negm; }
; #pragma unroll
;     for (int ks = 0; ks < DK / 16; ++ks) {
;       h16x8 k0 = *(const h16x8*)(ksm + r * KS + ks * 16 + hh * 8);
;       h16x8 k1 = *(const h16x8*)(ksm + (32 + r) * KS + ks * 16 + hh * 8);
;       st[0] = MFMA(k0, qf[ks], st[0]);
;       st[1] = MFMA(k1, qf[ks], st[1]);
;     }
;     float mx = fmaxf(st[0][0], st[1][0]);
; #pragma unroll
;     for (int i = 1; i < 16; ++i) mx = fmaxf(mx, fmaxf(st[0][i], st[1][i]));
;     mx = x32_max(mx);
;     if (__builtin_amdgcn_ballot_w64(mx > 8.f) != 0) {
;       const float dlt = fmaxf(mx, 0.f);
;       const float alpha = __builtin_amdgcn_exp2f(-dlt);
;       m += dlt;
;       lsum *= alpha;
; #pragma unroll
;       for (int i = 0; i < 16; ++i) { ot[0][i] *= alpha; ot[1][i] *= alpha; st[0][i] -= dlt; st[1][i] -= dlt; }
;     }
;     float ps = 0.f;
; #pragma unroll
;     for (int i = 0; i < 16; ++i) {
;       st[0][i] = __builtin_amdgcn_exp2f(st[0][i]);
;       st[1][i] = __builtin_amdgcn_exp2f(st[1][i]);
;       ps += st[0][i] + st[1][i];
;     }
;     lsum += ps;
; #pragma unroll
;     for (int s4 = 0; s4 < 4; ++s4) {
;       const int kt2 = s4 >> 1, hf = s4 & 1;
;       h16x8 pb;
; #pragma unroll
;       for (int j = 0; j < 8; ++j) pb[j] = (h16)st[kt2][8 * hf + j];
.Lgq_step4:
	s_waitcnt lgkmcnt(0)
	s_barrier
	ds_read_b128 v[194:197], v141 offset:36864
	ds_read_b128 v[198:201], v141 offset:41472
	ds_read_b128 v[230:233], v141 offset:36896
	ds_read_b128 v[234:237], v141 offset:41504
	v_exp_f32_e32 v48, v48
	v_exp_f32_e32 v49, v49
	v_exp_f32_e32 v50, v50
	v_exp_f32_e32 v51, v51
	s_waitcnt lgkmcnt(3)
	v_mfma_f32_32x32x16_f16 v[162:177], v[194:197], v[80:83], v[204:219]
	ds_read_b128 v[194:197], v141 offset:36928
	v_exp_f32_e32 v52, v52
	v_exp_f32_e32 v53, v53
	v_cvt_pk_f16_f32 v2, v48, v49
	v_exp_f32_e32 v54, v54
	v_exp_f32_e32 v55, v55
	v_cvt_pk_f16_f32 v3, v50, v51
	s_waitcnt lgkmcnt(3)
	v_mfma_f32_32x32x16_f16 v[178:193], v[198:201], v[80:83], v[204:219]
	ds_read_b128 v[198:201], v141 offset:41536
	v_exp_f32_e32 v56, v56
	v_exp_f32_e32 v57, v57
	v_cvt_pk_f16_f32 v4, v52, v53
	v_exp_f32_e32 v58, v58
	v_exp_f32_e32 v59, v59
	v_cvt_pk_f16_f32 v5, v54, v55
	s_waitcnt lgkmcnt(3)
	v_mfma_f32_32x32x16_f16 v[162:177], v[230:233], v[84:87], v[162:177]
	ds_read_b128 v[230:233], v141 offset:36960
	v_exp_f32_e32 v60, v60
	v_exp_f32_e32 v61, v61
	v_cvt_pk_f16_f32 v6, v56, v57
	v_exp_f32_e32 v62, v62
	v_exp_f32_e32 v63, v63
	v_cvt_pk_f16_f32 v7, v58, v59
	s_waitcnt lgkmcnt(3)
	v_mfma_f32_32x32x16_f16 v[178:193], v[234:237], v[84:87], v[178:193]
	ds_read_b128 v[234:237], v141 offset:41568
	v_exp_f32_e32 v64, v64
	v_exp_f32_e32 v65, v65
	v_cvt_pk_f16_f32 v8, v60, v61
	v_exp_f32_e32 v66, v66
	v_exp_f32_e32 v67, v67
	v_cvt_pk_f16_f32 v9, v62, v63
	s_waitcnt lgkmcnt(3)
	v_mfma_f32_32x32x16_f16 v[162:177], v[194:197], v[88:91], v[162:177]
	v_exp_f32_e32 v68, v68
	v_exp_f32_e32 v69, v69
	v_cvt_pk_f16_f32 v10, v64, v65
	v_exp_f32_e32 v70, v70
	v_exp_f32_e32 v71, v71
	v_cvt_pk_f16_f32 v11, v66, v67
	s_waitcnt lgkmcnt(2)
	v_mfma_f32_32x32x16_f16 v[178:193], v[198:201], v[88:91], v[178:193]
	v_exp_f32_e32 v72, v72
	v_exp_f32_e32 v73, v73
	v_cvt_pk_f16_f32 v12, v68, v69
	v_exp_f32_e32 v74, v74
	v_exp_f32_e32 v75, v75
	v_cvt_pk_f16_f32 v13, v70, v71
	s_waitcnt lgkmcnt(1)
	v_mfma_f32_32x32x16_f16 v[162:177], v[230:233], v[92:95], v[162:177]
	v_exp_f32_e32 v76, v76
	v_exp_f32_e32 v77, v77
	v_cvt_pk_f16_f32 v246, v72, v73
	v_exp_f32_e32 v78, v78
	v_exp_f32_e32 v79, v79
	v_cvt_pk_f16_f32 v247, v74, v75
	s_waitcnt lgkmcnt(0)
	v_mfma_f32_32x32x16_f16 v[178:193], v[234:237], v[92:95], v[178:193]
	v_cvt_pk_f16_f32 v248, v76, v77
	v_cvt_pk_f16_f32 v249, v78, v79
	s_add_i32 s40, s38, 2
	s_cmp_ge_u32 s40, s8
	s_cbranch_scc1 .Lgq_nw4
	s_add_i32 s40, s38, 3
	s_cmp_ge_u32 s40, s8
	s_cbranch_scc1 .Lgq_wz4
	s_waitcnt vmcnt(4)
	s_branch .Lgq_ww4

; #define MFMA(a, b, c) __builtin_amdgcn_mfma_f32_32x32x16_f16((a), (b), (c), 0, 0, 0)
; template <int DK, bool MLA>
; DI void attn_item(const h16* __restrict__ Q, const h16* __restrict__ Kp, const h16* __restrict__ Kr, const h16* __restrict__ Vt,
;                   int kbeg, int kend, h16* __restrict__ out, h16* sm) {
;     ...
;       *(u32x4*)(ksm + key * KS + part * 8) = RK[i];
;     }
; #pragma unroll
;     for (int i = 0; i < 2; ++i) {
;       const int c = tid + 256 * i, dv = c >> 3, kc = c & 7;
;       *(u32x4*)(vsm + dv * 72 + kc * 8) = RV[i];
;     }
;     __syncthreads();
;     if (it + 2 < ntile) ATT_GLOAD(RK, RV, kbeg + (it + 2) * 64)
;     f32x16 st[2];
;     const float negm = -m;
; #pragma unroll
;     for (int i = 0; i < 16; ++i) { st[0][i] = negm; st[1][i] = negm; }
; #pragma unroll
;     for (int ks = 0; ks < DK / 16; ++ks) {
;       h16x8 k0 = *(const h16x8*)(ksm + r * KS + ks * 16 + hh * 8);
;       h16x8 k1 = *(const h16x8*)(ksm + (32 + r) * KS + ks * 16 + hh * 8);
;       st[0] = MFMA(k0, qf[ks], st[0]);
;       st[1] = MFMA(k1, qf[ks], st[1]);
;     }
;     float mx = fmaxf(st[0][0], st[1][0]);
; #pragma unroll
;     for (int i = 1; i < 16; ++i) mx = fmaxf(mx, fmaxf(st[0][i], st[1][i]));
;     mx = x32_max(mx);
;     if (__builtin_amdgcn_ballot_w64(mx > 8.f) != 0) {
;       const float dlt = fmaxf(mx, 0.f);
;       const float alpha = __builtin_amdgcn_exp2f(-dlt);
;       m += dlt;
;       lsum *= alpha;
; #pragma unroll
;       for (int i = 0; i < 16; ++i) { ot[0][i] *= alpha; ot[1][i] *= alpha; st[0][i] -= dlt; st[1][i] -= dlt; }
;     }
;     float ps = 0.f;
; #pragma unroll
;     for (int i = 0; i < 16; ++i) {
;       st[0][i] = __builtin_amdgcn_exp2f(st[0][i]);
;       st[1][i] = __builtin_amdgcn_exp2f(st[1][i]);
;       ps += st[0][i] + st[1][i];
;     }
;     lsum += ps;
; #pragma unroll
;     for (int s4 = 0; s4 < 4; ++s4) {
;       const int kt2 = s4 >> 1, hf = s4 & 1;
;       h16x8 pb;
; #pragma unroll
;       for (int j = 0; j < 8; ++j) pb[j] = (h16)st[kt2][8 * hf + j];
;       const int kb = kt2 * 32 + 16 * hf;
; #pragma unroll
;       for (int dt = 0; dt < 2; ++dt) {
;         const h16* vp = vsm + (dt * 32 + r) * 72 + kb + 4 * hh;
;         h16x4 lo = *(const h16x4*)vp, hi = *(const h16x4*)(vp + 8);
;         h16x8 va = __builtin_shufflevector(lo, hi, 0, 1, 2, 3, 4, 5, 6, 7);
;         ot[dt] = MFMA(va, pb, ot[dt]);
;       }
.Lgq_ww4:
	ds_write_b128 v129, v[124:127] offset:0
	ds_write_b128 v131, v[120:123] offset:0
	ds_write_b128 v140, v[116:119] offset:9216
	ds_write_b128 v142, v[112:115] offset:9216
.Lgq_nw4:
	ds_read_b128 v[238:241], v143 offset:27648
	ds_read_b128 v[242:245], v143 offset:32256
	ds_read_b128 v[194:197], v143 offset:27680
	ds_read_b128 v[198:201], v143 offset:32288
	s_waitcnt lgkmcnt(3)
	v_mfma_f32_32x32x16_f16 v[32:47], v[238:241], v[2:5], v[32:47]
	ds_read_b128 v[238:241], v143 offset:27712
	s_add_i32 s40, s38, 4
	s_cmp_ge_u32 s40, s8
	s_cbranch_scc1 .Lgq_nl4
	s_lshl_b32 s40, s40, 7
	s_mov_b32 s41, 0
	global_load_dwordx4 v[124:127], v[220:221], off
	global_load_dwordx4 v[120:123], v[222:223], off
	v_lshl_add_u64 v[14:15], v[138:139], 0, s[40:41]
	v_lshl_add_u64 v[250:251], v[136:137], 0, s[40:41]
	global_load_dwordx4 v[116:119], v[14:15], off
	global_load_dwordx4 v[112:115], v[250:251], off
	v_lshl_add_u64 v[220:221], v[220:221], 0, v[228:229]
	v_lshl_add_u64 v[222:223], v[222:223], 0, v[228:229]
.Lgq_nl4:
	v_add_f32_e32 v226, v48, v49
	v_add_f32_e32 v226, v226, v50
	v_add_f32_e32 v226, v226, v51
	v_add_f32_e32 v226, v226, v52
	s_waitcnt lgkmcnt(3)
	v_mfma_f32_32x32x16_f16 v[16:31], v[242:245], v[2:5], v[16:31]
	ds_read_b128 v[242:245], v143 offset:32320
	v_add_f32_e32 v226, v226, v53
	v_add_f32_e32 v226, v226, v54
	v_add_f32_e32 v226, v226, v55
	v_add_f32_e32 v227, v56, v57
	v_add_f32_e32 v227, v227, v58
	v_add_f32_e32 v227, v227, v59
	v_add_f32_e32 v227, v227, v60
	v_add_f32_e32 v227, v227, v61
	s_waitcnt lgkmcnt(3)
	v_mfma_f32_32x32x16_f16 v[32:47], v[194:197], v[6:9], v[32:47]
	ds_read_b128 v[194:197], v143 offset:27744
	v_add_f32_e32 v227, v227, v62
	v_add_f32_e32 v227, v227, v63
	v_add_f32_e32 v250, v64, v65
	v_add_f32_e32 v250, v250, v66
	v_add_f32_e32 v250, v250, v67
	v_add_f32_e32 v250, v250, v68
	v_add_f32_e32 v250, v250, v69
	v_add_f32_e32 v250, v250, v70
	s_waitcnt lgkmcnt(3)
	v_mfma_f32_32x32x16_f16 v[16:31], v[198:201], v[6:9], v[16:31]
	ds_read_b128 v[198:201], v143 offset:32352
	v_add_f32_e32 v250, v250, v71
	v_add_f32_e32 v251, v72, v73
	v_add_f32_e32 v251, v251, v74
	v_add_f32_e32 v251, v251, v75
	v_add_f32_e32 v251, v251, v76
	v_add_f32_e32 v251, v251, v77
	v_add_f32_e32 v251, v251, v78
	v_add_f32_e32 v251, v251, v79
	s_waitcnt lgkmcnt(3)
	v_mfma_f32_32x32x16_f16 v[32:47], v[238:241], v[10:13], v[32:47]
	v_add_f32_e32 v226, v226, v227
	v_add_f32_e32 v250, v250, v251
	v_add_f32_e32 v226, v226, v250
	v_add_f32_e32 v153, v153, v226
	v_max3_f32 v0, v162, v163, v164
	v_max3_f32 v14, v165, v166, v167
	s_waitcnt lgkmcnt(2)
	v_mfma_f32_32x32x16_f16 v[16:31], v[242:245], v[10:13], v[16:31]
	v_max3_f32 v15, v168, v169, v170
	v_max3_f32 v202, v171, v172, v173
	v_max3_f32 v0, v0, v174, v175
	v_max3_f32 v14, v14, v176, v177
	v_max3_f32 v15, v15, v178, v179
	v_max3_f32 v202, v202, v180, v181
	s_waitcnt lgkmcnt(1)
	v_mfma_f32_32x32x16_f16 v[32:47], v[194:197], v[246:249], v[32:47]
	v_max3_f32 v0, v0, v182, v183
	v_max3_f32 v14, v14, v184, v185
	v_max3_f32 v15, v15, v186, v187
	v_max3_f32 v202, v202, v188, v189
	v_max3_f32 v0, v0, v190, v191
	v_max3_f32 v14, v14, v192, v193
	v_max3_f32 v0, v0, v14, v15
	s_waitcnt lgkmcnt(0)
	v_mfma_f32_32x32x16_f16 v[16:31], v[198:201], v[246:249], v[16:31]
	v_max_f32_e32 v0, v0, v202
	v_mov_b32_e32 v14, v0
	s_nop 1
	v_permlane32_swap_b32_e32 v0, v14
	v_max_f32_e32 v0, v0, v14
	v_cmp_lt_f32_e32 vcc, s79, v0
	s_cbranch_vccnz .Lgq_rare4

; #define MFMA(a, b, c) __builtin_amdgcn_mfma_f32_32x32x16_f16((a), (b), (c), 0, 0, 0)
; template <int DK, bool MLA>
; DI void attn_item(const h16* __restrict__ Q, const h16* __restrict__ Kp, const h16* __restrict__ Kr, const h16* __restrict__ Vt,
;                   int kbeg, int kend, h16* __restrict__ out, h16* sm) {
;     ...
;     f32x16 st[2];
;     const float negm = -m;
; #pragma unroll
;     for (int i = 0; i < 16; ++i) { st[0][i] = negm; st[1][i] = negm; }
; #pragma unroll
;     for (int ks = 0; ks < DK / 16; ++ks) {
;       h16x8 k0 = *(const h16x8*)(ksm + r * KS + ks * 16 + hh * 8);
;       h16x8 k1 = *(const h16x8*)(ksm + (32 + r) * KS + ks * 16 + hh * 8);
;       st[0] = MFMA(k0, qf[ks], st[0]);
;       st[1] = MFMA(k1, qf[ks], st[1]);
;     }
;     float mx = fmaxf(st[0][0], st[1][0]);
; #pragma unroll
;     for (int i = 1; i < 16; ++i) mx = fmaxf(mx, fmaxf(st[0][i], st[1][i]));
;     mx = x32_max(mx);
;     if (__builtin_amdgcn_ballot_w64(mx > 8.f) != 0) {
;       const float dlt = fmaxf(mx, 0.f);
;       const float alpha = __builtin_amdgcn_exp2f(-dlt);
;       m += dlt;
;       lsum *= alpha;
; #pragma unroll
;       for (int i = 0; i < 16; ++i) { ot[0][i] *= alpha; ot[1][i] *= alpha; st[0][i] -= dlt; st[1][i] -= dlt; }
;     }
;     float ps = 0.f;
; #pragma unroll
;     for (int i = 0; i < 16; ++i) {
;       st[0][i] = __builtin_amdgcn_exp2f(st[0][i]);
;       st[1][i] = __builtin_amdgcn_exp2f(st[1][i]);
;       ps += st[0][i] + st[1][i];
;     }
;     lsum += ps;
; #pragma unroll
;     for (int s4 = 0; s4 < 4; ++s4) {
;       const int kt2 = s4 >> 1, hf = s4 & 1;
;       h16x8 pb;
; #pragma unroll
;       for (int j = 0; j < 8; ++j) pb[j] = (h16)st[kt2][8 * hf + j];
.Lgq_step5:
	s_waitcnt lgkmcnt(0)
	s_barrier
	ds_read_b128 v[194:197], v141 offset:0
	ds_read_b128 v[198:201], v141 offset:4608
	ds_read_b128 v[230:233], v141 offset:32
	ds_read_b128 v[234:237], v141 offset:4640
	v_exp_f32_e32 v162, v162
	v_exp_f32_e32 v163, v163
	v_exp_f32_e32 v164, v164
	v_exp_f32_e32 v165, v165
	s_waitcnt lgkmcnt(3)
	v_mfma_f32_32x32x16_f16 v[48:63], v[194:197], v[80:83], v[204:219]
	ds_read_b128 v[194:197], v141 offset:64
	v_exp_f32_e32 v166, v166
	v_exp_f32_e32 v167, v167
	v_cvt_pk_f16_f32 v2, v162, v163
	v_exp_f32_e32 v168, v168
	v_exp_f32_e32 v169, v169
	v_cvt_pk_f16_f32 v3, v164, v165
	s_waitcnt lgkmcnt(3)
	v_mfma_f32_32x32x16_f16 v[64:79], v[198:201], v[80:83], v[204:219]
	ds_read_b128 v[198:201], v141 offset:4672
	v_exp_f32_e32 v170, v170
	v_exp_f32_e32 v171, v171
	v_cvt_pk_f16_f32 v4, v166, v167
	v_exp_f32_e32 v172, v172
	v_exp_f32_e32 v173, v173
	v_cvt_pk_f16_f32 v5, v168, v169
	s_waitcnt lgkmcnt(3)
	v_mfma_f32_32x32x16_f16 v[48:63], v[230:233], v[84:87], v[48:63]
	ds_read_b128 v[230:233], v141 offset:96
	v_exp_f32_e32 v174, v174
	v_exp_f32_e32 v175, v175
	v_cvt_pk_f16_f32 v6, v170, v171
	v_exp_f32_e32 v176, v176
	v_exp_f32_e32 v177, v177
	v_cvt_pk_f16_f32 v7, v172, v173
	s_waitcnt lgkmcnt(3)
	v_mfma_f32_32x32x16_f16 v[64:79], v[234:237], v[84:87], v[64:79]
	ds_read_b128 v[234:237], v141 offset:4704
	v_exp_f32_e32 v178, v178
	v_exp_f32_e32 v179, v179
	v_cvt_pk_f16_f32 v8, v174, v175
	v_exp_f32_e32 v180, v180
	v_exp_f32_e32 v181, v181
	v_cvt_pk_f16_f32 v9, v176, v177
	s_waitcnt lgkmcnt(3)
	v_mfma_f32_32x32x16_f16 v[48:63], v[194:197], v[88:91], v[48:63]
	v_exp_f32_e32 v182, v182
	v_exp_f32_e32 v183, v183
	v_cvt_pk_f16_f32 v10, v178, v179
	v_exp_f32_e32 v184, v184
	v_exp_f32_e32 v185, v185
	v_cvt_pk_f16_f32 v11, v180, v181
	s_waitcnt lgkmcnt(2)
	v_mfma_f32_32x32x16_f16 v[64:79], v[198:201], v[88:91], v[64:79]
	v_exp_f32_e32 v186, v186
	v_exp_f32_e32 v187, v187
	v_cvt_pk_f16_f32 v12, v182, v183
	v_exp_f32_e32 v188, v188
	v_exp_f32_e32 v189, v189
	v_cvt_pk_f16_f32 v13, v184, v185
	s_waitcnt lgkmcnt(1)
	v_mfma_f32_32x32x16_f16 v[48:63], v[230:233], v[92:95], v[48:63]
	v_exp_f32_e32 v190, v190
	v_exp_f32_e32 v191, v191
	v_cvt_pk_f16_f32 v246, v186, v187
	v_exp_f32_e32 v192, v192
	v_exp_f32_e32 v193, v193
	v_cvt_pk_f16_f32 v247, v188, v189
	s_waitcnt lgkmcnt(0)
	v_mfma_f32_32x32x16_f16 v[64:79], v[234:237], v[92:95], v[64:79]
	v_cvt_pk_f16_f32 v248, v190, v191
	v_cvt_pk_f16_f32 v249, v192, v193
	s_add_i32 s40, s38, 2
	s_cmp_ge_u32 s40, s8
	s_cbranch_scc1 .Lgq_nw5
	s_add_i32 s40, s38, 3
	s_cmp_ge_u32 s40, s8
	s_cbranch_scc1 .Lgq_wz5
	s_waitcnt vmcnt(4)
	s_branch .Lgq_ww5

; #define MFMA(a, b, c) __builtin_amdgcn_mfma_f32_32x32x16_f16((a), (b), (c), 0, 0, 0)
; template <int DK, bool MLA>
; DI void attn_item(const h16* __restrict__ Q, const h16* __restrict__ Kp, const h16* __restrict__ Kr, const h16* __restrict__ Vt,
;                   int kbeg, int kend, h16* __restrict__ out, h16* sm) {
;     ...
;       *(u32x4*)(ksm + key * KS + part * 8) = RK[i];
;     }
; #pragma unroll
;     for (int i = 0; i < 2; ++i) {
;       const int c = tid + 256 * i, dv = c >> 3, kc = c & 7;
;       *(u32x4*)(vsm + dv * 72 + kc * 8) = RV[i];
;     }
;     __syncthreads();
;     if (it + 2 < ntile) ATT_GLOAD(RK, RV, kbeg + (it + 2) * 64)
;     f32x16 st[2];
;     const float negm = -m;
; #pragma unroll
;     for (int i = 0; i < 16; ++i) { st[0][i] = negm; st[1][i] = negm; }
; #pragma unroll
;     for (int ks = 0; ks < DK / 16; ++ks) {
;       h16x8 k0 = *(const h16x8*)(ksm + r * KS + ks * 16 + hh * 8);
;       h16x8 k1 = *(const h16x8*)(ksm + (32 + r) * KS + ks * 16 + hh * 8);
;       st[0] = MFMA(k0, qf[ks], st[0]);
;       st[1] = MFMA(k1, qf[ks], st[1]);
;     }
;     float mx = fmaxf(st[0][0], st[1][0]);
; #pragma unroll
;     for (int i = 1; i < 16; ++i) mx = fmaxf(mx, fmaxf(st[0][i], st[1][i]));
;     mx = x32_max(mx);
;     if (__builtin_amdgcn_ballot_w64(mx > 8.f) != 0) {
;       const float dlt = fmaxf(mx, 0.f);
;       const float alpha = __builtin_amdgcn_exp2f(-dlt);
;       m += dlt;
;       lsum *= alpha;
; #pragma unroll
;       for (int i = 0; i < 16; ++i) { ot[0][i] *= alpha; ot[1][i] *= alpha; st[0][i] -= dlt; st[1][i] -= dlt; }
;     }
;     float ps = 0.f;
; #pragma unroll
;     for (int i = 0; i < 16; ++i) {
;       st[0][i] = __builtin_amdgcn_exp2f(st[0][i]);
;       st[1][i] = __builtin_amdgcn_exp2f(st[1][i]);
;       ps += st[0][i] + st[1][i];
;     }
;     lsum += ps;
; #pragma unroll
;     for (int s4 = 0; s4 < 4; ++s4) {
;       const int kt2 = s4 >> 1, hf = s4 & 1;
;       h16x8 pb;
; #pragma unroll
;       for (int j = 0; j < 8; ++j) pb[j] = (h16)st[kt2][8 * hf + j];
;       const int kb = kt2 * 32 + 16 * hf;
; #pragma unroll
;       for (int dt = 0; dt < 2; ++dt) {
;         const h16* vp = vsm + (dt * 32 + r) * 72 + kb + 4 * hh;
;         h16x4 lo = *(const h16x4*)vp, hi = *(const h16x4*)(vp + 8);
;         h16x8 va = __builtin_shufflevector(lo, hi, 0, 1, 2, 3, 4, 5, 6, 7);
;         ot[dt] = MFMA(va, pb, ot[dt]);
;       }
.Lgq_ww5:
	ds_write_b128 v129, v[100:103] offset:18432
	ds_write_b128 v131, v[96:99] offset:18432
	ds_write_b128 v140, v[108:111] offset:27648
	ds_write_b128 v142, v[104:107] offset:27648
.Lgq_nw5:
	ds_read_b128 v[238:241], v143 offset:46080
	ds_read_b128 v[242:245], v143 offset:50688
	ds_read_b128 v[194:197], v143 offset:46112
	ds_read_b128 v[198:201], v143 offset:50720
	s_waitcnt lgkmcnt(3)
	v_mfma_f32_32x32x16_f16 v[32:47], v[238:241], v[2:5], v[32:47]
	ds_read_b128 v[238:241], v143 offset:46144
	s_add_i32 s40, s38, 4
	s_cmp_ge_u32 s40, s8
	s_cbranch_scc1 .Lgq_nl5
	s_lshl_b32 s40, s40, 7
	s_mov_b32 s41, 0
	global_load_dwordx4 v[100:103], v[220:221], off
	global_load_dwordx4 v[96:99], v[222:223], off
	v_lshl_add_u64 v[14:15], v[134:135], 0, s[40:41]
	v_lshl_add_u64 v[250:251], v[132:133], 0, s[40:41]
	global_load_dwordx4 v[108:111], v[14:15], off
	global_load_dwordx4 v[104:107], v[250:251], off
	v_lshl_add_u64 v[220:221], v[220:221], 0, v[228:229]
	v_lshl_add_u64 v[222:223], v[222:223], 0, v[228:229]
.Lgq_nl5:
	v_add_f32_e32 v226, v162, v163
	v_add_f32_e32 v226, v226, v164
	v_add_f32_e32 v226, v226, v165
	v_add_f32_e32 v226, v226, v166
	s_waitcnt lgkmcnt(3)
	v_mfma_f32_32x32x16_f16 v[16:31], v[242:245], v[2:5], v[16:31]
	ds_read_b128 v[242:245], v143 offset:50752
	v_add_f32_e32 v226, v226, v167
	v_add_f32_e32 v226, v226, v168
	v_add_f32_e32 v226, v226, v169
	v_add_f32_e32 v227, v170, v171
	v_add_f32_e32 v227, v227, v172
	v_add_f32_e32 v227, v227, v173
	v_add_f32_e32 v227, v227, v174
	v_add_f32_e32 v227, v227, v175
	s_waitcnt lgkmcnt(3)
	v_mfma_f32_32x32x16_f16 v[32:47], v[194:197], v[6:9], v[32:47]
	ds_read_b128 v[194:197], v143 offset:46176
	v_add_f32_e32 v227, v227, v176
	v_add_f32_e32 v227, v227, v177
	v_add_f32_e32 v250, v178, v179
	v_add_f32_e32 v250, v250, v180
	v_add_f32_e32 v250, v250, v181
	v_add_f32_e32 v250, v250, v182
	v_add_f32_e32 v250, v250, v183
	v_add_f32_e32 v250, v250, v184
	s_waitcnt lgkmcnt(3)
	v_mfma_f32_32x32x16_f16 v[16:31], v[198:201], v[6:9], v[16:31]
	ds_read_b128 v[198:201], v143 offset:50784
	v_add_f32_e32 v250, v250, v185
	v_add_f32_e32 v251, v186, v187
	v_add_f32_e32 v251, v251, v188
	v_add_f32_e32 v251, v251, v189
	v_add_f32_e32 v251, v251, v190
	v_add_f32_e32 v251, v251, v191
	v_add_f32_e32 v251, v251, v192
	v_add_f32_e32 v251, v251, v193
	s_waitcnt lgkmcnt(3)
	v_mfma_f32_32x32x16_f16 v[32:47], v[238:241], v[10:13], v[32:47]
	v_add_f32_e32 v226, v226, v227
	v_add_f32_e32 v250, v250, v251
	v_add_f32_e32 v226, v226, v250
	v_add_f32_e32 v153, v153, v226
	v_max3_f32 v0, v48, v49, v50
	v_max3_f32 v14, v51, v52, v53
	s_waitcnt lgkmcnt(2)
	v_mfma_f32_32x32x16_f16 v[16:31], v[242:245], v[10:13], v[16:31]
	v_max3_f32 v15, v54, v55, v56
	v_max3_f32 v202, v57, v58, v59
	v_max3_f32 v0, v0, v60, v61
	v_max3_f32 v14, v14, v62, v63
	v_max3_f32 v15, v15, v64, v65
	v_max3_f32 v202, v202, v66, v67
	s_waitcnt lgkmcnt(1)
	v_mfma_f32_32x32x16_f16 v[32:47], v[194:197], v[246:249], v[32:47]
	v_max3_f32 v0, v0, v68, v69
	v_max3_f32 v14, v14, v70, v71
	v_max3_f32 v15, v15, v72, v73
	v_max3_f32 v202, v202, v74, v75
	v_max3_f32 v0, v0, v76, v77
	v_max3_f32 v14, v14, v78, v79
	v_max3_f32 v0, v0, v14, v15
	s_waitcnt lgkmcnt(0)
	v_mfma_f32_32x32x16_f16 v[16:31], v[198:201], v[246:249], v[16:31]
	v_max_f32_e32 v0, v0, v202
	v_mov_b32_e32 v14, v0
	s_nop 1
	v_permlane32_swap_b32_e32 v0, v14
	v_max_f32_e32 v0, v0, v14
	v_cmp_lt_f32_e32 vcc, s79, v0
	s_cbranch_vccnz .Lgq_rare5
.Lgq_cont5:
	s_add_i32 s38, s38, 1
	s_branch .Lgq_step0
.Lgq_rare0:
	s_nop 7
	s_nop 7
	s_nop 7
	v_max_f32_e32 v0, 0, v0
	v_exp_f32_e64 v14, -v0
	v_add_f32_e32 v147, v147, v0
	v_xor_b32_e32 v204, 0x80000000, v147
	v_mov_b32_e32 v205, v204
	v_mov_b32_e32 v206, v204
	v_mov_b32_e32 v207, v204
	v_mov_b32_e32 v208, v204
	v_mov_b32_e32 v209, v204
	v_mov_b32_e32 v210, v204
	v_mov_b32_e32 v211, v204
	v_mov_b32_e32 v212, v204
	v_mov_b32_e32 v213, v204
	v_mov_b32_e32 v214, v204
	v_mov_b32_e32 v215, v204
	v_mov_b32_e32 v216, v204
	v_mov_b32_e32 v217, v204
	v_mov_b32_e32 v218, v204
	v_mov_b32_e32 v219, v204
	v_mul_f32_e32 v153, v153, v14
	v_sub_f32_e32 v162, v162, v0
	v_sub_f32_e32 v163, v163, v0
	v_sub_f32_e32 v164, v164, v0
	v_sub_f32_e32 v165, v165, v0
	v_sub_f32_e32 v166, v166, v0
	v_sub_f32_e32 v167, v167, v0
	v_sub_f32_e32 v168, v168, v0
	v_sub_f32_e32 v169, v169, v0
	v_sub_f32_e32 v170, v170, v0
	v_sub_f32_e32 v171, v171, v0
	v_sub_f32_e32 v172, v172, v0
	v_sub_f32_e32 v173, v173, v0
	v_sub_f32_e32 v174, v174, v0
	v_sub_f32_e32 v175, v175, v0
	v_sub_f32_e32 v176, v176, v0
	v_sub_f32_e32 v177, v177, v0
	v_sub_f32_e32 v178, v178, v0
	v_sub_f32_e32 v179, v179, v0
	v_sub_f32_e32 v180, v180, v0
	v_sub_f32_e32 v181, v181, v0
	v_sub_f32_e32 v182, v182, v0
	v_sub_f32_e32 v183, v183, v0
	v_sub_f32_e32 v184, v184, v0
	v_sub_f32_e32 v185, v185, v0
	v_sub_f32_e32 v186, v186, v0
	v_sub_f32_e32 v187, v187, v0
	v_sub_f32_e32 v188, v188, v0
	v_sub_f32_e32 v189, v189, v0
	v_sub_f32_e32 v190, v190, v0
	v_sub_f32_e32 v191, v191, v0
	v_sub_f32_e32 v192, v192, v0
	v_sub_f32_e32 v193, v193, v0
	v_mul_f32_e32 v32, v32, v14
	v_mul_f32_e32 v33, v33, v14
	v_mul_f32_e32 v34, v34, v14
	v_mul_f32_e32 v35, v35, v14
	v_mul_f32_e32 v36, v36, v14
	v_mul_f32_e32 v37, v37, v14
	v_mul_f32_e32 v38, v38, v14
	v_mul_f32_e32 v39, v39, v14
	v_mul_f32_e32 v40, v40, v14
	v_mul_f32_e32 v41, v41, v14
	v_mul_f32_e32 v42, v42, v14
	v_mul_f32_e32 v43, v43, v14
	v_mul_f32_e32 v44, v44, v14
	v_mul_f32_e32 v45, v45, v14
	v_mul_f32_e32 v46, v46, v14
	v_mul_f32_e32 v47, v47, v14
	v_mul_f32_e32 v16, v16, v14
	v_mul_f32_e32 v17, v17, v14
	v_mul_f32_e32 v18, v18, v14
	v_mul_f32_e32 v19, v19, v14
	v_mul_f32_e32 v20, v20, v14
	v_mul_f32_e32 v21, v21, v14
	v_mul_f32_e32 v22, v22, v14
	v_mul_f32_e32 v23, v23, v14
	v_mul_f32_e32 v24, v24, v14
	v_mul_f32_e32 v25, v25, v14
	v_mul_f32_e32 v26, v26, v14
	v_mul_f32_e32 v27, v27, v14
	v_mul_f32_e32 v28, v28, v14
	v_mul_f32_e32 v29, v29, v14
	v_mul_f32_e32 v30, v30, v14
	v_mul_f32_e32 v31, v31, v14
	s_branch .Lgq_cont0

; #define MFMA(a, b, c) __builtin_amdgcn_mfma_f32_32x32x16_f16((a), (b), (c), 0, 0, 0)
; template <int DK, bool MLA>
; DI void attn_item(const h16* __restrict__ Q, const h16* __restrict__ Kp, const h16* __restrict__ Kr, const h16* __restrict__ Vt,
;                   int kbeg, int kend, h16* __restrict__ out, h16* sm) {
;     ...
; #pragma unroll
;     for (int i = 0; i < 16; ++i) {
;       st[0][i] = __builtin_amdgcn_exp2f(st[0][i]);
;       st[1][i] = __builtin_amdgcn_exp2f(st[1][i]);
;       ps += st[0][i] + st[1][i];
;     }
;     lsum += ps;
; #pragma unroll
;     for (int s4 = 0; s4 < 4; ++s4) {
;       const int kt2 = s4 >> 1, hf = s4 & 1;
;       h16x8 pb;
; #pragma unroll
;       for (int j = 0; j < 8; ++j) pb[j] = (h16)st[kt2][8 * hf + j];
;       const int kb = kt2 * 32 + 16 * hf;
; #pragma unroll
;       for (int dt = 0; dt < 2; ++dt) {
;         const h16* vp = vsm + (dt * 32 + r) * 72 + kb + 4 * hh;
;         h16x4 lo = *(const h16x4*)vp, hi = *(const h16x4*)(vp + 8);
;         h16x8 va = __builtin_shufflevector(lo, hi, 0, 1, 2, 3, 4, 5, 6, 7);
;         ot[dt] = MFMA(va, pb, ot[dt]);
;       }
;     }
.Lgq_drain0:
	ds_read_b128 v[238:241], v143 offset:9216
	ds_read_b128 v[242:245], v143 offset:13824
	ds_read_b128 v[194:197], v143 offset:9248
	ds_read_b128 v[198:201], v143 offset:13856
	v_exp_f32_e32 v162, v162
	v_exp_f32_e32 v163, v163
	v_exp_f32_e32 v164, v164
	v_exp_f32_e32 v165, v165
	v_exp_f32_e32 v166, v166
	v_exp_f32_e32 v167, v167
	v_exp_f32_e32 v168, v168
	v_exp_f32_e32 v169, v169
	v_cvt_pk_f16_f32 v2, v162, v163
	v_cvt_pk_f16_f32 v3, v164, v165
	v_exp_f32_e32 v170, v170
	v_exp_f32_e32 v171, v171
	v_exp_f32_e32 v172, v172
	v_exp_f32_e32 v173, v173
	v_cvt_pk_f16_f32 v4, v166, v167
	v_cvt_pk_f16_f32 v5, v168, v169
	v_exp_f32_e32 v174, v174
	v_exp_f32_e32 v175, v175
	v_exp_f32_e32 v176, v176
	v_exp_f32_e32 v177, v177
	v_cvt_pk_f16_f32 v6, v170, v171
	v_cvt_pk_f16_f32 v7, v172, v173
	v_exp_f32_e32 v178, v178
	v_exp_f32_e32 v179, v179
	v_exp_f32_e32 v180, v180
	v_exp_f32_e32 v181, v181
	v_cvt_pk_f16_f32 v8, v174, v175
	v_cvt_pk_f16_f32 v9, v176, v177
	v_exp_f32_e32 v182, v182
	v_exp_f32_e32 v183, v183
	v_exp_f32_e32 v184, v184
	v_exp_f32_e32 v185, v185
	v_cvt_pk_f16_f32 v10, v178, v179
	v_cvt_pk_f16_f32 v11, v180, v181
	v_exp_f32_e32 v186, v186
	v_exp_f32_e32 v187, v187
	v_exp_f32_e32 v188, v188
	v_exp_f32_e32 v189, v189
	v_cvt_pk_f16_f32 v12, v182, v183
	v_cvt_pk_f16_f32 v13, v184, v185
	v_exp_f32_e32 v190, v190
	v_exp_f32_e32 v191, v191
	v_exp_f32_e32 v192, v192
	v_exp_f32_e32 v193, v193
	v_cvt_pk_f16_f32 v246, v186, v187
	v_cvt_pk_f16_f32 v247, v188, v189
	v_cvt_pk_f16_f32 v248, v190, v191
	v_cvt_pk_f16_f32 v249, v192, v193
	s_nop 1
	s_waitcnt lgkmcnt(3)
	v_mfma_f32_32x32x16_f16 v[32:47], v[238:241], v[2:5], v[32:47]
	ds_read_b128 v[238:241], v143 offset:9280
	v_add_f32_e32 v226, v162, v163
	v_add_f32_e32 v226, v226, v164
	v_add_f32_e32 v226, v226, v165
	v_add_f32_e32 v226, v226, v166
	s_waitcnt lgkmcnt(3)
	v_mfma_f32_32x32x16_f16 v[16:31], v[242:245], v[2:5], v[16:31]
	ds_read_b128 v[242:245], v143 offset:13888
	v_add_f32_e32 v226, v226, v167
	v_add_f32_e32 v226, v226, v168
	v_add_f32_e32 v226, v226, v169
	v_add_f32_e32 v227, v170, v171
	s_waitcnt lgkmcnt(3)
	v_mfma_f32_32x32x16_f16 v[32:47], v[194:197], v[6:9], v[32:47]
	ds_read_b128 v[194:197], v143 offset:9312
	v_add_f32_e32 v227, v227, v172
	v_add_f32_e32 v227, v227, v173
	v_add_f32_e32 v227, v227, v174
	v_add_f32_e32 v227, v227, v175
	s_waitcnt lgkmcnt(3)
	v_mfma_f32_32x32x16_f16 v[16:31], v[198:201], v[6:9], v[16:31]
	ds_read_b128 v[198:201], v143 offset:13920
	v_add_f32_e32 v227, v227, v176
	v_add_f32_e32 v227, v227, v177
	v_add_f32_e32 v250, v178, v179
	v_add_f32_e32 v250, v250, v180
	s_waitcnt lgkmcnt(3)
	v_mfma_f32_32x32x16_f16 v[32:47], v[238:241], v[10:13], v[32:47]
	v_add_f32_e32 v250, v250, v181
	v_add_f32_e32 v250, v250, v182
	v_add_f32_e32 v250, v250, v183
	v_add_f32_e32 v250, v250, v184
	s_waitcnt lgkmcnt(2)
	v_mfma_f32_32x32x16_f16 v[16:31], v[242:245], v[10:13], v[16:31]
	v_add_f32_e32 v250, v250, v185
	v_add_f32_e32 v251, v186, v187
	v_add_f32_e32 v251, v251, v188
	v_add_f32_e32 v251, v251, v189
	s_waitcnt lgkmcnt(1)
	v_mfma_f32_32x32x16_f16 v[32:47], v[194:197], v[246:249], v[32:47]
	v_add_f32_e32 v251, v251, v190
	v_add_f32_e32 v251, v251, v191
	v_add_f32_e32 v251, v251, v192
	v_add_f32_e32 v251, v251, v193
	s_waitcnt lgkmcnt(0)
	v_mfma_f32_32x32x16_f16 v[16:31], v[198:201], v[246:249], v[16:31]
	v_add_f32_e32 v226, v226, v227
	v_add_f32_e32 v250, v250, v251
	v_add_f32_e32 v226, v226, v250
	v_add_f32_e32 v153, v153, v226
	s_branch .LBB0_2743
.Lgq_drain1:
	ds_read_b128 v[238:241], v143 offset:27648
	ds_read_b128 v[242:245], v143 offset:32256
	ds_read_b128 v[194:197], v143 offset:27680
	ds_read_b128 v[198:201], v143 offset:32288
	v_exp_f32_e32 v162, v162
	v_exp_f32_e32 v163, v163
	v_exp_f32_e32 v164, v164
	v_exp_f32_e32 v165, v165
	v_exp_f32_e32 v166, v166
	v_exp_f32_e32 v167, v167
	v_exp_f32_e32 v168, v168
	v_exp_f32_e32 v169, v169
	v_cvt_pk_f16_f32 v2, v162, v163
	v_cvt_pk_f16_f32 v3, v164, v165
	v_exp_f32_e32 v170, v170
	v_exp_f32_e32 v171, v171
	v_exp_f32_e32 v172, v172
	v_exp_f32_e32 v173, v173
	v_cvt_pk_f16_f32 v4, v166, v167
	v_cvt_pk_f16_f32 v5, v168, v169
	v_exp_f32_e32 v174, v174
	v_exp_f32_e32 v175, v175
	v_exp_f32_e32 v176, v176
	v_exp_f32_e32 v177, v177
	v_cvt_pk_f16_f32 v6, v170, v171
	v_cvt_pk_f16_f32 v7, v172, v173
	v_exp_f32_e32 v178, v178
	v_exp_f32_e32 v179, v179
	v_exp_f32_e32 v180, v180
	v_exp_f32_e32 v181, v181
	v_cvt_pk_f16_f32 v8, v174, v175
	v_cvt_pk_f16_f32 v9, v176, v177
	v_exp_f32_e32 v182, v182
	v_exp_f32_e32 v183, v183
	v_exp_f32_e32 v184, v184
	v_exp_f32_e32 v185, v185
	v_cvt_pk_f16_f32 v10, v178, v179
	v_cvt_pk_f16_f32 v11, v180, v181
	v_exp_f32_e32 v186, v186
	v_exp_f32_e32 v187, v187
	v_exp_f32_e32 v188, v188
	v_exp_f32_e32 v189, v189
	v_cvt_pk_f16_f32 v12, v182, v183
	v_cvt_pk_f16_f32 v13, v184, v185
	v_exp_f32_e32 v190, v190
	v_exp_f32_e32 v191, v191
	v_exp_f32_e32 v192, v192
	v_exp_f32_e32 v193, v193
	v_cvt_pk_f16_f32 v246, v186, v187
	v_cvt_pk_f16_f32 v247, v188, v189
	v_cvt_pk_f16_f32 v248, v190, v191
	v_cvt_pk_f16_f32 v249, v192, v193
	s_nop 1
	s_waitcnt lgkmcnt(3)
	v_mfma_f32_32x32x16_f16 v[32:47], v[238:241], v[2:5], v[32:47]
	ds_read_b128 v[238:241], v143 offset:27712
	v_add_f32_e32 v226, v162, v163
	v_add_f32_e32 v226, v226, v164
	v_add_f32_e32 v226, v226, v165
	v_add_f32_e32 v226, v226, v166
	s_waitcnt lgkmcnt(3)
	v_mfma_f32_32x32x16_f16 v[16:31], v[242:245], v[2:5], v[16:31]
	ds_read_b128 v[242:245], v143 offset:32320
	v_add_f32_e32 v226, v226, v167
	v_add_f32_e32 v226, v226, v168
	v_add_f32_e32 v226, v226, v169
	v_add_f32_e32 v227, v170, v171
	s_waitcnt lgkmcnt(3)
	v_mfma_f32_32x32x16_f16 v[32:47], v[194:197], v[6:9], v[32:47]
	ds_read_b128 v[194:197], v143 offset:27744
	v_add_f32_e32 v227, v227, v172
	v_add_f32_e32 v227, v227, v173
	v_add_f32_e32 v227, v227, v174
	v_add_f32_e32 v227, v227, v175
	s_waitcnt lgkmcnt(3)
	v_mfma_f32_32x32x16_f16 v[16:31], v[198:201], v[6:9], v[16:31]
	ds_read_b128 v[198:201], v143 offset:32352
	v_add_f32_e32 v227, v227, v176
	v_add_f32_e32 v227, v227, v177
	v_add_f32_e32 v250, v178, v179
	v_add_f32_e32 v250, v250, v180
	s_waitcnt lgkmcnt(3)
	v_mfma_f32_32x32x16_f16 v[32:47], v[238:241], v[10:13], v[32:47]
	v_add_f32_e32 v250, v250, v181
	v_add_f32_e32 v250, v250, v182
	v_add_f32_e32 v250, v250, v183
	v_add_f32_e32 v250, v250, v184
	s_waitcnt lgkmcnt(2)
	v_mfma_f32_32x32x16_f16 v[16:31], v[242:245], v[10:13], v[16:31]
	v_add_f32_e32 v250, v250, v185
	v_add_f32_e32 v251, v186, v187
	v_add_f32_e32 v251, v251, v188
	v_add_f32_e32 v251, v251, v189
	s_waitcnt lgkmcnt(1)
	v_mfma_f32_32x32x16_f16 v[32:47], v[194:197], v[246:249], v[32:47]
	v_add_f32_e32 v251, v251, v190
	v_add_f32_e32 v251, v251, v191
	v_add_f32_e32 v251, v251, v192
	v_add_f32_e32 v251, v251, v193
	s_waitcnt lgkmcnt(0)
	v_mfma_f32_32x32x16_f16 v[16:31], v[198:201], v[246:249], v[16:31]
	v_add_f32_e32 v226, v226, v227
	v_add_f32_e32 v250, v250, v251
	v_add_f32_e32 v226, v226, v250
	v_add_f32_e32 v153, v153, v226
	s_branch .LBB0_2743
; #define MFMA(a, b, c) __builtin_amdgcn_mfma_f32_32x32x16_f16((a), (b), (c), 0, 0, 0)
; template <int DK, bool MLA>
; DI void attn_item(const h16* __restrict__ Q, const h16* __restrict__ Kp, const h16* __restrict__ Kr, const h16* __restrict__ Vt,
;                   int kbeg, int kend, h16* __restrict__ out, h16* sm) {
;     ...
; #pragma unroll
;     for (int i = 0; i < 16; ++i) {
;       st[0][i] = __builtin_amdgcn_exp2f(st[0][i]);
;       st[1][i] = __builtin_amdgcn_exp2f(st[1][i]);
;       ps += st[0][i] + st[1][i];
;     }
;     lsum += ps;
; #pragma unroll
;     for (int s4 = 0; s4 < 4; ++s4) {
;       const int kt2 = s4 >> 1, hf = s4 & 1;
;       h16x8 pb;
; #pragma unroll
;       for (int j = 0; j < 8; ++j) pb[j] = (h16)st[kt2][8 * hf + j];
;       const int kb = kt2 * 32 + 16 * hf;
; #pragma unroll
;       for (int dt = 0; dt < 2; ++dt) {
;         const h16* vp = vsm + (dt * 32 + r) * 72 + kb + 4 * hh;
;         h16x4 lo = *(const h16x4*)vp, hi = *(const h16x4*)(vp + 8);
;         h16x8 va = __builtin_shufflevector(lo, hi, 0, 1, 2, 3, 4, 5, 6, 7);
;         ot[dt] = MFMA(va, pb, ot[dt]);
;       }
;     }
.Lgq_drain2:
	ds_read_b128 v[238:241], v143 offset:46080
	ds_read_b128 v[242:245], v143 offset:50688
	ds_read_b128 v[194:197], v143 offset:46112
	ds_read_b128 v[198:201], v143 offset:50720
	v_exp_f32_e32 v162, v162
	v_exp_f32_e32 v163, v163
	v_exp_f32_e32 v164, v164
	v_exp_f32_e32 v165, v165
	v_exp_f32_e32 v166, v166
	v_exp_f32_e32 v167, v167
	v_exp_f32_e32 v168, v168
	v_exp_f32_e32 v169, v169
	v_cvt_pk_f16_f32 v2, v162, v163
	v_cvt_pk_f16_f32 v3, v164, v165
	v_exp_f32_e32 v170, v170
	v_exp_f32_e32 v171, v171
	v_exp_f32_e32 v172, v172
	v_exp_f32_e32 v173, v173
	v_cvt_pk_f16_f32 v4, v166, v167
	v_cvt_pk_f16_f32 v5, v168, v169
	v_exp_f32_e32 v174, v174
	v_exp_f32_e32 v175, v175
	v_exp_f32_e32 v176, v176
	v_exp_f32_e32 v177, v177
	v_cvt_pk_f16_f32 v6, v170, v171
	v_cvt_pk_f16_f32 v7, v172, v173
	v_exp_f32_e32 v178, v178
	v_exp_f32_e32 v179, v179
	v_exp_f32_e32 v180, v180
	v_exp_f32_e32 v181, v181
	v_cvt_pk_f16_f32 v8, v174, v175
	v_cvt_pk_f16_f32 v9, v176, v177
	v_exp_f32_e32 v182, v182
	v_exp_f32_e32 v183, v183
	v_exp_f32_e32 v184, v184
	v_exp_f32_e32 v185, v185
	v_cvt_pk_f16_f32 v10, v178, v179
	v_cvt_pk_f16_f32 v11, v180, v181
	v_exp_f32_e32 v186, v186
	v_exp_f32_e32 v187, v187
	v_exp_f32_e32 v188, v188
	v_exp_f32_e32 v189, v189
	v_cvt_pk_f16_f32 v12, v182, v183
	v_cvt_pk_f16_f32 v13, v184, v185
	v_exp_f32_e32 v190, v190
	v_exp_f32_e32 v191, v191
	v_exp_f32_e32 v192, v192
	v_exp_f32_e32 v193, v193
	v_cvt_pk_f16_f32 v246, v186, v187
	v_cvt_pk_f16_f32 v247, v188, v189
	v_cvt_pk_f16_f32 v248, v190, v191
	v_cvt_pk_f16_f32 v249, v192, v193
	s_nop 1
	s_waitcnt lgkmcnt(3)
	v_mfma_f32_32x32x16_f16 v[32:47], v[238:241], v[2:5], v[32:47]
	ds_read_b128 v[238:241], v143 offset:46144
	v_add_f32_e32 v226, v162, v163
	v_add_f32_e32 v226, v226, v164
	v_add_f32_e32 v226, v226, v165
	v_add_f32_e32 v226, v226, v166
	s_waitcnt lgkmcnt(3)
	v_mfma_f32_32x32x16_f16 v[16:31], v[242:245], v[2:5], v[16:31]
	ds_read_b128 v[242:245], v143 offset:50752
	v_add_f32_e32 v226, v226, v167
	v_add_f32_e32 v226, v226, v168
	v_add_f32_e32 v226, v226, v169
	v_add_f32_e32 v227, v170, v171
	s_waitcnt lgkmcnt(3)
	v_mfma_f32_32x32x16_f16 v[32:47], v[194:197], v[6:9], v[32:47]
	ds_read_b128 v[194:197], v143 offset:46176
	v_add_f32_e32 v227, v227, v172
	v_add_f32_e32 v227, v227, v173
	v_add_f32_e32 v227, v227, v174
	v_add_f32_e32 v227, v227, v175
	s_waitcnt lgkmcnt(3)
	v_mfma_f32_32x32x16_f16 v[16:31], v[198:201], v[6:9], v[16:31]
	ds_read_b128 v[198:201], v143 offset:50784
	v_add_f32_e32 v227, v227, v176
	v_add_f32_e32 v227, v227, v177
	v_add_f32_e32 v250, v178, v179
	v_add_f32_e32 v250, v250, v180
	s_waitcnt lgkmcnt(3)
	v_mfma_f32_32x32x16_f16 v[32:47], v[238:241], v[10:13], v[32:47]
	v_add_f32_e32 v250, v250, v181
	v_add_f32_e32 v250, v250, v182
	v_add_f32_e32 v250, v250, v183
	v_add_f32_e32 v250, v250, v184
	s_waitcnt lgkmcnt(2)
	v_mfma_f32_32x32x16_f16 v[16:31], v[242:245], v[10:13], v[16:31]
	v_add_f32_e32 v250, v250, v185
	v_add_f32_e32 v251, v186, v187
	v_add_f32_e32 v251, v251, v188
	v_add_f32_e32 v251, v251, v189
	s_waitcnt lgkmcnt(1)
	v_mfma_f32_32x32x16_f16 v[32:47], v[194:197], v[246:249], v[32:47]
	v_add_f32_e32 v251, v251, v190
	v_add_f32_e32 v251, v251, v191
	v_add_f32_e32 v251, v251, v192
	v_add_f32_e32 v251, v251, v193
	s_waitcnt lgkmcnt(0)
	v_mfma_f32_32x32x16_f16 v[16:31], v[198:201], v[246:249], v[16:31]
	v_add_f32_e32 v226, v226, v227
	v_add_f32_e32 v250, v250, v251
	v_add_f32_e32 v226, v226, v250
	v_add_f32_e32 v153, v153, v226
	s_branch .LBB0_2743
